# chain finalize reductions via DPP; retention and DeltaNet chunk loops: loop-top waits count the 16 younger output stores (no wait on the previous chunk's store acks), full wait only before the first t
# baseline (speedup 1.0000x reference)
; DI void ret_chain(const Params& p, int layer, int chain, char* lds) {
;     ...
;   asm volatile("" : "+v"(tid_));
;   const int tid = tid_, wave = tid >> 6, lane = tid & 63, r = lane & 31, h = lane >> 5;
;   const int wm = wave >> 1, wn = wave & 1;
;   const int b = chain >> 3, hh = (chain >> 1) & 3, dir = chain & 1;
;   constexpr int L4 = 40;
;   u16* qA = (u16*)lds;
;   u16* kA = qA + 64 * L4;
;   u16* ks = kA + 64 * L4;
;   u16* vs = ks + 64 * LS;
;   u16* QK = vs + 64 * LS;
;   u16* Rt = QK + 64 * LS;
;   const u16* QC = (const u16*)(p.ws + O_QC);
;   const u16* KC = (const u16*)(p.ws + O_KC);
;   const u16* Z = (const u16*)(p.ws + O_Z);
;   u16* OUT = dir ? (u16*)(p.ws + O_ORB) : (u16*)(p.ws + O_ACT) + 512;
;   const int opitch = dir ? 256 : AP;
;   const int lc = tid >> 2, lp4 = (tid & 3) * 8;
;   const int vc = tid >> 3, vp = (tid & 7) * 8;
;   const float lg = log1pf(-expf(p.ret_l1m[layer * 8 + dir * 4 + hh]));
;   f32x16 R = zero16();
;   auto rowof = [&](int n, int c) -> int {
;     int cn, base, len;
;     if (n < 4) { cn = n; base = NLAT + b * LC; len = LC; } else { cn = n - 4; base = b * TT; len = TT; }
;     int pos = cn * 64 + c;
;     return base + (dir ? len - 1 - pos : pos);
;   };
;   uint4 pq, pk, pv0, pv1;
;     ...
;   RET_LOAD(0);
.LBB0_633:
	s_add_i32 s0, s39, 0xffffff80
	s_lshr_b32 s2, s0, 3
	s_bfe_u32 s3, s39, 0x20001
	s_bfe_u32 s5, s38, 0x10008
	s_cmp_eq_u32 s5, 0
	s_cselect_b64 vcc, -1, 0
	s_and_b64 s[0:1], vcc, exec
	s_mov_b32 s0, 0x50cc500
	s_cselect_b32 s4, s0, 0x3c08c100
	s_cselect_b32 s43, s61, 0x100
	s_lshl_b32 s0, s5, 2
	v_readlane_b32 s1, v252, 34
	s_or_b32 s0, s0, s1
	v_readlane_b32 s24, v252, 20
	v_readlane_b32 s25, v252, 21
	s_or_b32 s24, s0, s3
	v_readlane_b32 s8, v250, 0
	s_lshl_b64 s[0:1], s[24:25], 2
	v_readlane_b32 s16, v250, 8
	v_readlane_b32 s17, v250, 9
	s_add_u32 s0, s16, s0
	v_mov_b32_e32 v6, v248
	s_addc_u32 s1, s17, s1
	global_load_dword v13, v1, s[0:1]
	s_mov_b32 s0, 0x3fb8aa3b
	v_ashrrev_i32_e32 v96, 2, v6
	v_sub_u32_e32 v0, 0xff, v96
	s_lshl_b32 s42, s2, 8
	v_cndmask_b32_e32 v2, v0, v96, vcc
	s_or_b32 s45, s42, 0x10000
	v_add_u32_e32 v2, s45, v2
	v_readlane_b32 s9, v250, 1
	v_ashrrev_i32_e32 v3, 31, v2
	v_readlane_b32 s6, v251, 5
	v_lshlrev_b64 v[2:3], 8, v[2:3]
	v_readlane_b32 s7, v251, 6
	v_readlane_b32 s8, v251, 50
	s_lshl_b32 s24, s3, 6
	v_lshl_add_u64 v[14:15], s[6:7], 0, v[2:3]
	v_readlane_b32 s9, v251, 51
	v_lshlrev_b32_e32 v0, 3, v6
	v_and_b32_e32 v8, 24, v0
	v_lshlrev_b32_e32 v0, 1, v8
	v_ashrrev_i32_e32 v97, 3, v6
	s_waitcnt vmcnt(8)
	v_add_u32_e32 v98, 32, v97
	s_lshl_b32 s36, s3, 7
	s_mov_b32 s37, s25
	s_movk_i32 s5, 0x50
	s_add_u32 s6, s6, s24
	s_addc_u32 s7, s7, 0
	v_ashrrev_i32_e32 v12, 7, v6
	v_lshl_add_u64 v[68:69], s[6:7], 0, v[0:1]
	v_and_b32_e32 v10, 31, v6
	v_bfe_u32 v7, v6, 5, 1
	v_bfe_u32 v11, v6, 6, 1
	v_lshrrev_b32_e32 v9, 6, v6
	v_readlane_b32 s10, v250, 2
	v_readlane_b32 s11, v250, 3
	v_readlane_b32 s12, v250, 4
	v_readlane_b32 s13, v250, 5
	v_readlane_b32 s14, v250, 6
	v_readlane_b32 s15, v250, 7
	v_readlane_b32 s18, v250, 10
	v_readlane_b32 s19, v250, 11
	v_readlane_b32 s20, v250, 12
	v_readlane_b32 s21, v250, 13
	v_readlane_b32 s22, v250, 14
	v_readlane_b32 s23, v250, 15
	v_mul_u32_u24_e32 v107, 0x480, v7
	s_mov_b32 s44, 0
	s_mov_b32 s47, 0
	s_waitcnt vmcnt(0)
	v_mul_f32_e32 v4, 0x3fb8aa3b, v13
	v_fma_f32 v5, v13, s0, -v4
	v_rndne_f32_e32 v16, v4
	v_fmac_f32_e32 v5, 0x32a5705f, v13
	v_sub_f32_e32 v4, v4, v16
	v_add_f32_e32 v4, v4, v5
	v_cvt_i32_f32_e32 v16, v16
	v_exp_f32_e32 v17, v4
	s_mov_b32 s0, 0xc2ce8ed0
	v_lshl_add_u64 v[4:5], s[8:9], 0, v[2:3]
	v_lshl_add_u64 v[2:3], v[14:15], 0, s[24:25]
	v_ldexp_f32 v14, v17, v16
	v_cmp_ngt_f32_e64 s[0:1], s0, v13
	v_lshl_add_u64 v[2:3], v[2:3], 0, v[0:1]
	v_lshl_add_u64 v[4:5], v[4:5], 0, s[24:25]
	v_cndmask_b32_e64 v14, 0, v14, s[0:1]
	s_mov_b32 s0, 0x42b17218
	v_cmp_nlt_f32_e64 s[0:1], s0, v13
	v_lshl_add_u64 v[4:5], v[4:5], 0, v[0:1]
	global_load_dwordx4 v[50:53], v[2:3], off
	global_load_dwordx4 v[54:57], v[4:5], off
	v_cndmask_b32_e64 v13, v215, v14, s[0:1]
	v_sub_f32_e32 v16, 1.0, v13
	v_add_f32_e32 v17, -1.0, v16
	v_frexp_mant_f32_e32 v18, v16
	v_cvt_f64_f32_e32 v[14:15], v16
	s_mov_b32 s0, 0x3f2aaaab
	v_sub_f32_e32 v19, v17, v16
	v_frexp_exp_i32_f64_e32 v14, v[14:15]
	v_cmp_gt_f32_e64 s[0:1], s0, v18
	v_sub_f32_e64 v17, -v13, v17
	v_add_f32_e32 v15, 1.0, v19
	v_subbrev_co_u32_e64 v14, s[0:1], 0, v14, s[0:1]
	v_add_f32_e32 v15, v17, v15
	v_sub_u32_e32 v17, 0, v14
	v_cvt_f32_i32_e32 v14, v14
	v_ldexp_f32 v16, v16, v17
	v_ldexp_f32 v15, v15, v17
	v_add_f32_e32 v17, -1.0, v16
	v_add_f32_e32 v18, 1.0, v16
	v_add_f32_e32 v19, 1.0, v17
	v_add_f32_e32 v20, -1.0, v18
	v_sub_f32_e32 v19, v16, v19
	v_sub_f32_e32 v16, v16, v20
	v_mul_f32_e32 v20, 0x3f317218, v14
	v_add_f32_e32 v19, v15, v19
	v_add_f32_e32 v15, v15, v16
	s_mov_b32 s0, 0x3f317218
	v_fma_f32 v16, v14, s0, -v20
	v_add_f32_e32 v21, v17, v19
	v_add_f32_e32 v22, v18, v15
	v_fmac_f32_e32 v16, 0xb102e308, v14
	v_sub_f32_e32 v14, v21, v17
	v_sub_f32_e32 v17, v22, v18
	v_rcp_f32_e32 v18, v22
	v_add_f32_e32 v23, v20, v16
	v_sub_f32_e32 v15, v15, v17
	v_sub_f32_e32 v17, v23, v20
	v_sub_f32_e32 v16, v16, v17
	v_mul_f32_e32 v17, v21, v18
	v_sub_f32_e32 v14, v19, v14
	v_mul_f32_e32 v19, v22, v17
	v_fma_f32 v20, v17, v22, -v19
	v_fmac_f32_e32 v20, v17, v15
	v_add_f32_e32 v24, v19, v20
	v_sub_f32_e32 v25, v21, v24
	v_sub_f32_e32 v19, v24, v19
	v_sub_f32_e32 v21, v21, v25
	v_sub_f32_e32 v19, v19, v20
	v_sub_f32_e32 v20, v21, v24
	v_add_f32_e32 v14, v14, v20
	v_add_f32_e32 v14, v19, v14
	v_add_f32_e32 v19, v25, v14
	v_mul_f32_e32 v20, v18, v19
	v_sub_f32_e32 v21, v25, v19
	v_mul_f32_e32 v24, v22, v20
	v_add_f32_e32 v14, v14, v21
	v_add_f32_e32 v21, v17, v20
	v_fma_f32 v22, v20, v22, -v24
	v_sub_f32_e32 v17, v21, v17
	v_fmac_f32_e32 v22, v20, v15
	v_sub_f32_e32 v15, v20, v17
	v_add_f32_e32 v17, v24, v22
	v_sub_f32_e32 v20, v17, v24
	v_sub_f32_e32 v24, v19, v17
	v_sub_f32_e32 v19, v19, v24
	v_sub_f32_e32 v17, v19, v17
	v_sub_f32_e32 v20, v20, v22
	v_add_f32_e32 v14, v14, v17
	v_add_f32_e32 v14, v20, v14
	v_add_f32_e32 v14, v24, v14
	v_mul_f32_e32 v14, v18, v14
	v_add_f32_e32 v14, v15, v14
	v_add_f32_e32 v15, v21, v14
	v_mul_f32_e32 v17, v15, v15
	v_fmamk_f32 v20, v17, 0x3e9b6dac, v216
	v_sub_f32_e32 v18, v15, v21
	v_ldexp_f32 v19, v15, 1
	v_mul_f32_e32 v15, v15, v17
	v_fmaak_f32 v17, v17, v20, 0x3f2aaada
	v_mul_f32_e32 v15, v15, v17
	v_add_f32_e32 v17, v19, v15
	v_sub_f32_e32 v14, v14, v18
	v_sub_f32_e32 v18, v17, v19
	v_ldexp_f32 v14, v14, 1
	v_sub_f32_e32 v15, v15, v18
	v_add_f32_e32 v14, v14, v15
	v_add_f32_e32 v15, v17, v14
	v_sub_f32_e32 v17, v15, v17
	v_add_f32_e32 v18, v23, v15
	v_sub_f32_e32 v14, v14, v17
	v_sub_f32_e32 v17, v18, v23
	v_sub_f32_e32 v19, v18, v17
	v_sub_f32_e32 v15, v15, v17
	v_add_f32_e32 v17, v16, v14
	v_sub_f32_e32 v19, v23, v19
	v_sub_f32_e32 v20, v17, v16
	v_add_f32_e32 v15, v15, v19
; DI int crow(int reg, int h) { return (reg & 3) + 8 * (reg >> 2) + 4 * h; }
; DI void ret_chain(const Params& p, int layer, int chain, char* lds) {
;     ...
;   const int lc = tid >> 2, lp4 = (tid & 3) * 8;
;   const int vc = tid >> 3, vp = (tid & 7) * 8;
;   const float lg = log1pf(-expf(p.ret_l1m[layer * 8 + dir * 4 + hh]));
;   f32x16 R = zero16();
;   auto rowof = [&](int n, int c) -> int {
;     int cn, base, len;
;     if (n < 4) { cn = n; base = NLAT + b * LC; len = LC; } else { cn = n - 4; base = b * TT; len = TT; }
;     int pos = cn * 64 + c;
;     return base + (dir ? len - 1 - pos : pos);
;   };
;   uint4 pq, pk, pv0, pv1;
;     ...
;   RET_LOAD(0);
;   for (int n = 0; n < 68; ++n) {
;     __syncthreads();
;     *(uint4*)(qA + lc * L4 + lp4) = pq;
;     *(uint4*)(kA + lc * L4 + lp4) = pk;
;     st8s(ks + lc * L4 + lp4, pk, __expf((float)(63 - lc) * lg));
;     *(uint4*)(vs + vc * LS + vp) = pv0;
;     *(uint4*)(vs + (vc + 32) * LS + vp) = pv1;
;     if (wm == 0) st_transp(Rt, L4, R, wm, wn, r, h);
;     if (n + 1 < 68) RET_LOAD(n + 1);
;     __syncthreads();
;     {
;       f32x16 qk = mm64<2>(qA, L4, kA, L4, wm, wn, r, h);
;       const int s = wn * 32 + r;
; #pragma unroll
;       for (int g = 0; g < 16; ++g) {
;         int c = wm * 32 + crow(g, h);
;         qk[g] = (s <= c) ? qk[g] * __expf((float)(c - s) * lg) : 0.f;
;       }
;       st_transp(QK, LS, qk, wm, wn, r, h);
;     }
;     __syncthreads();
;     {
;       f32x16 o1 = mm64x<4, true, true>(QK, LS, vs, LS, wm, wn, r, h, lane);
;       f32x16 o2 = mm64<2>(qA, L4, Rt, L4, wm, wn, r, h);
;       const float gch = __expf(64.f * lg);
; #pragma unroll
;       for (int g = 0; g < 16; ++g) {
;         int c = wm * 32 + crow(g, h);
;         float ov = o1[g] + __expf((float)(c + 1) * lg) * o2[g];
	v_sub_f32_e32 v19, v17, v20
	v_sub_f32_e32 v14, v14, v20
	v_sub_f32_e32 v16, v16, v19
	v_add_f32_e32 v15, v17, v15
	v_add_f32_e32 v14, v14, v16
	v_add_f32_e32 v16, v18, v15
	v_sub_f32_e32 v17, v16, v18
	v_sub_f32_e32 v15, v15, v17
	v_add_f32_e32 v14, v14, v15
	v_add_f32_e32 v14, v16, v14
	v_cmp_nlt_f32_e64 s[0:1], 1.0, v13
	v_mov_b32_e32 v15, 0x7fc00000
	v_sub_u32_e32 v2, 0xff, v97
	v_cndmask_b32_e64 v14, v15, v14, s[0:1]
	v_cmp_neq_f32_e64 s[0:1], 1.0, v13
	v_sub_u32_e32 v16, 0xdf, v97
	v_cndmask_b32_e32 v2, v2, v97, vcc
	v_cndmask_b32_e64 v14, v217, v14, s[0:1]
	s_mov_b32 s0, 0x33800000
	v_cndmask_b32_e32 v16, v16, v98, vcc
	v_cmp_lt_f32_e64 s[0:1], |v13|, s0
	v_add_u32_e32 v2, s45, v2
	v_mov_b64_e32 v[4:5], s[50:51]
	v_add_u32_e32 v16, s45, v16
	v_cndmask_b32_e64 v13, v14, -v13, s[0:1]
	v_mad_i64_i32 v[2:3], s[0:1], v2, s87, v[4:5]
	v_mad_i64_i32 v[4:5], s[0:1], v16, s87, v[4:5]
	v_sub_u32_e32 v16, 63, v96
	v_lshl_add_u64 v[14:15], v[2:3], 0, s[36:37]
	v_lshlrev_b32_e32 v2, 4, v6
	v_cvt_f32_i32_e32 v16, v16
	v_and_b32_e32 v2, 0x70, v2
	v_mov_b32_e32 v3, v1
	v_lshl_add_u64 v[4:5], v[4:5], 0, s[36:37]
	v_lshl_add_u64 v[14:15], v[14:15], 0, v[2:3]
	v_lshl_add_u64 v[4:5], v[4:5], 0, v[2:3]
	global_load_dwordx4 v[58:61], v[14:15], off offset:3616
	global_load_dwordx4 v[62:65], v[4:5], off offset:3616
	v_mul_lo_u32 v4, v96, s5
	v_add3_u32 v99, s88, v4, v0
	v_mul_f32_e32 v4, v13, v16
	v_writelane_b32 v252, s24, 20
	s_add_u32 s6, s8, s24
	v_mul_f32_e32 v4, 0x3fb8aa3b, v4
	s_addc_u32 s7, s9, 0
	v_lshlrev_b32_e32 v14, 5, v12
	v_exp_f32_e32 v66, v4
	v_mul_lo_u32 v4, v97, s60
	v_lshl_add_u64 v[70:71], s[6:7], 0, v[0:1]
	v_or_b32_e32 v0, v14, v10
	v_add3_u32 v100, s88, v4, v2
	v_mul_lo_u32 v0, v0, s5
	v_lshlrev_b32_e32 v4, 4, v7
	v_lshl_or_b32 v16, v11, 5, v10
	v_add3_u32 v102, s88, v0, v4
	v_mul_u32_u24_e32 v0, 40, v16
	v_lshlrev_b32_e32 v0, 1, v0
	v_mov_b32_e32 v17, s88
	v_lshlrev_b32_e32 v15, 3, v7
	v_add3_u32 v103, s88, v0, v4
	v_mad_u32_u24 v0, v16, s60, v17
	v_lshlrev_b32_e32 v4, 6, v12
	v_bfe_u32 v12, v6, 2, 2
	s_movk_i32 s0, 0x80
	v_add3_u32 v104, v0, v4, v15
	v_mad_u32_u24 v5, v12, s60, v17
	v_lshlrev_b32_e32 v0, 1, v6
	v_cmp_gt_u32_e64 s[0:1], s0, v6
	v_and_b32_e32 v6, 32, v0
	v_add_u32_e32 v0, v5, v4
	v_add3_u32 v105, v0, v6, v8
	v_lshlrev_b32_e32 v0, 6, v11
	s_add_u32 s3, s84, s4
	v_add_u32_e32 v4, v5, v0
	s_addc_u32 s4, s85, 0
	s_lshl_b32 s41, s2, 12
	v_add3_u32 v106, v4, v6, v8
	v_mul_f32_e32 v4, 0x42800000, v13
	s_add_u32 s2, s3, s36
	v_mul_f32_e32 v4, 0x3fb8aa3b, v4
	s_addc_u32 s3, s4, 0
	v_exp_f32_e32 v72, v4
	v_lshl_add_u64 v[4:5], s[2:3], 0, v[0:1]
	v_lshlrev_b32_e32 v0, 1, v10
	v_lshl_or_b32 v110, v7, 2, v14
	v_lshl_add_u64 v[74:75], v[4:5], 0, v[0:1]
	v_sub_u32_e32 v4, v110, v16
	v_cvt_f32_i32_e32 v4, v4
	v_lshl_or_b32 v0, v9, 5, v10
	v_mul_lo_u32 v0, v0, s5
	v_add3_u32 v109, s88, v0, v15
	v_mad_u32_u24 v0, v12, s5, v17
	v_or_b32_e32 v111, 1, v110
	v_add3_u32 v17, v0, v6, v8
	v_mul_f32_e32 v0, v13, v4
	v_sub_u32_e32 v4, v111, v16
	v_cvt_f32_i32_e32 v4, v4
	v_mul_f32_e32 v0, 0x3fb8aa3b, v0
	v_or_b32_e32 v112, 2, v110
	v_exp_f32_e32 v76, v0
	v_mul_f32_e32 v0, v13, v4
	v_sub_u32_e32 v4, v112, v16
	v_cvt_f32_i32_e32 v4, v4
	v_mul_f32_e32 v0, 0x3fb8aa3b, v0
	v_or_b32_e32 v113, 3, v110
	v_exp_f32_e32 v77, v0
	v_mul_f32_e32 v0, v13, v4
	v_sub_u32_e32 v4, v113, v16
	v_cvt_f32_i32_e32 v4, v4
	v_mul_f32_e32 v0, 0x3fb8aa3b, v0
	v_or_b32_e32 v114, 8, v110
	v_exp_f32_e32 v78, v0
	v_mul_f32_e32 v0, v13, v4
	v_sub_u32_e32 v4, v114, v16
	v_cvt_f32_i32_e32 v4, v4
	v_mul_f32_e32 v0, 0x3fb8aa3b, v0
	v_or_b32_e32 v115, 9, v110
	v_exp_f32_e32 v79, v0
	v_mul_f32_e32 v0, v13, v4
	v_sub_u32_e32 v4, v115, v16
	v_cvt_f32_i32_e32 v4, v4
	v_mul_f32_e32 v0, 0x3fb8aa3b, v0
	v_or_b32_e32 v116, 10, v110
	v_exp_f32_e32 v80, v0
	v_mul_f32_e32 v0, v13, v4
	v_sub_u32_e32 v4, v116, v16
	v_cvt_f32_i32_e32 v4, v4
	v_mul_f32_e32 v0, 0x3fb8aa3b, v0
	v_or_b32_e32 v117, 11, v110
	v_exp_f32_e32 v81, v0
	v_mul_f32_e32 v0, v13, v4
	v_sub_u32_e32 v4, v117, v16
	v_cvt_f32_i32_e32 v4, v4
	v_mul_f32_e32 v0, 0x3fb8aa3b, v0
	v_or_b32_e32 v118, 16, v110
	v_exp_f32_e32 v82, v0
	v_mul_f32_e32 v0, v13, v4
	v_sub_u32_e32 v4, v118, v16
	v_cvt_f32_i32_e32 v4, v4
	v_mul_f32_e32 v0, 0x3fb8aa3b, v0
	v_or_b32_e32 v119, 17, v110
	v_exp_f32_e32 v83, v0
	v_mul_f32_e32 v0, v13, v4
	v_sub_u32_e32 v4, v119, v16
	v_cvt_f32_i32_e32 v4, v4
	v_mul_f32_e32 v0, 0x3fb8aa3b, v0
	v_or_b32_e32 v120, 18, v110
	v_exp_f32_e32 v84, v0
	v_mul_f32_e32 v0, v13, v4
	v_sub_u32_e32 v4, v120, v16
	v_cvt_f32_i32_e32 v4, v4
; DI int crow(int reg, int h) { return (reg & 3) + 8 * (reg >> 2) + 4 * h; }
; DI void ret_chain(const Params& p, int layer, int chain, char* lds) {
;     ...
;       f32x16 qk = mm64<2>(qA, L4, kA, L4, wm, wn, r, h);
;       const int s = wn * 32 + r;
; #pragma unroll
;       for (int g = 0; g < 16; ++g) {
;         int c = wm * 32 + crow(g, h);
;         qk[g] = (s <= c) ? qk[g] * __expf((float)(c - s) * lg) : 0.f;
;       }
;       st_transp(QK, LS, qk, wm, wn, r, h);
;     }
;     __syncthreads();
;     {
;       f32x16 o1 = mm64x<4, true, true>(QK, LS, vs, LS, wm, wn, r, h, lane);
;       f32x16 o2 = mm64<2>(qA, L4, Rt, L4, wm, wn, r, h);
;       const float gch = __expf(64.f * lg);
; #pragma unroll
;       for (int g = 0; g < 16; ++g) {
;         int c = wm * 32 + crow(g, h);
;         float ov = o1[g] + __expf((float)(c + 1) * lg) * o2[g];
	v_mul_f32_e32 v0, 0x3fb8aa3b, v0
	v_or_b32_e32 v121, 19, v110
	v_exp_f32_e32 v85, v0
	v_mul_f32_e32 v0, v13, v4
	v_sub_u32_e32 v4, v121, v16
	v_cvt_f32_i32_e32 v4, v4
	v_mul_f32_e32 v0, 0x3fb8aa3b, v0
	v_or_b32_e32 v122, 24, v110
	v_exp_f32_e32 v86, v0
	v_mul_f32_e32 v0, v13, v4
	v_sub_u32_e32 v4, v122, v16
	v_cvt_f32_i32_e32 v4, v4
	v_mul_f32_e32 v0, 0x3fb8aa3b, v0
	v_or_b32_e32 v123, 25, v110
	v_exp_f32_e32 v87, v0
	v_mul_f32_e32 v0, v13, v4
	v_sub_u32_e32 v4, v123, v16
	v_cvt_f32_i32_e32 v4, v4
	v_mul_f32_e32 v0, 0x3fb8aa3b, v0
	v_or_b32_e32 v124, 26, v110
	v_exp_f32_e32 v88, v0
	v_mul_f32_e32 v0, v13, v4
	v_sub_u32_e32 v4, v124, v16
	v_cvt_f32_i32_e32 v4, v4
	v_mul_f32_e32 v0, 0x3fb8aa3b, v0
	v_or_b32_e32 v125, 27, v110
	v_exp_f32_e32 v89, v0
	v_mul_f32_e32 v0, v13, v4
	v_sub_u32_e32 v4, v125, v16
	v_cvt_f32_i32_e32 v4, v4
	v_mul_f32_e32 v0, 0x3fb8aa3b, v0
	v_exp_f32_e32 v90, v0
	s_add_u32 s36, s50, s36
	v_mul_f32_e32 v0, v13, v4
	v_mul_f32_e32 v0, 0x3fb8aa3b, v0
	v_exp_f32_e32 v91, v0
	v_cvt_f32_i32_e32 v0, v112
	v_cvt_f32_i32_e32 v4, v111
	v_or_b32_e32 v11, 4, v15
	s_addc_u32 s37, s51, 0
	v_mul_f32_e32 v0, v13, v0
	v_mul_f32_e32 v0, 0x3fb8aa3b, v0
	v_exp_f32_e32 v127, v0
	v_add_u32_e32 v0, 4, v110
	v_cvt_f32_i32_e32 v0, v0
	v_mul_f32_e32 v4, v13, v4
	v_mul_f32_e32 v4, 0x3fb8aa3b, v4
	v_exp_f32_e32 v126, v4
	v_cvt_f32_i32_e32 v4, v113
	v_mul_f32_e32 v0, v13, v0
	v_mul_f32_e32 v0, 0x3fb8aa3b, v0
	v_exp_f32_e32 v129, v0
	v_cvt_f32_i32_e32 v0, v116
	v_mul_f32_e32 v4, v13, v4
	v_mul_f32_e32 v4, 0x3fb8aa3b, v4
	v_exp_f32_e32 v128, v4
	v_cvt_f32_i32_e32 v4, v115
	v_mul_f32_e32 v0, v13, v0
	v_mul_f32_e32 v0, 0x3fb8aa3b, v0
	v_exp_f32_e32 v131, v0
	v_add_u32_e32 v0, 12, v110
	v_mul_f32_e32 v4, v13, v4
	v_cvt_f32_i32_e32 v0, v0
	v_mul_f32_e32 v4, 0x3fb8aa3b, v4
	v_exp_f32_e32 v130, v4
	v_cvt_f32_i32_e32 v4, v117
	v_mul_f32_e32 v0, v13, v0
	v_mul_f32_e32 v0, 0x3fb8aa3b, v0
	v_exp_f32_e32 v133, v0
	v_mul_f32_e32 v4, v13, v4
	v_cvt_f32_i32_e32 v0, v120
	v_mul_f32_e32 v4, 0x3fb8aa3b, v4
	v_exp_f32_e32 v132, v4
	v_cvt_f32_i32_e32 v4, v119
	v_mul_f32_e32 v0, v13, v0
	v_mul_f32_e32 v0, 0x3fb8aa3b, v0
	v_exp_f32_e32 v135, v0
	v_mul_f32_e32 v4, v13, v4
	v_add_u32_e32 v0, 20, v110
	v_mul_f32_e32 v4, 0x3fb8aa3b, v4
	v_cvt_f32_i32_e32 v0, v0
	v_exp_f32_e32 v134, v4
	v_cvt_f32_i32_e32 v4, v121
	v_mul_u32_u24_e32 v108, 0x90, v11
	v_mul_f32_e32 v0, v13, v0
	v_mul_f32_e32 v0, 0x3fb8aa3b, v0
	v_mul_f32_e32 v4, v13, v4
	v_mul_f32_e32 v4, 0x3fb8aa3b, v4
	v_exp_f32_e32 v137, v0
	v_cvt_f32_i32_e32 v0, v124
	v_exp_f32_e32 v136, v4
	v_cvt_f32_i32_e32 v4, v123
	v_mul_u32_u24_e32 v18, 0x280, v7
	v_mul_f32_e32 v0, v13, v0
	v_mul_f32_e32 v0, 0x3fb8aa3b, v0
	v_mul_f32_e32 v4, v13, v4
	v_mul_f32_e32 v4, 0x3fb8aa3b, v4
	v_exp_f32_e32 v139, v0
	v_add_u32_e32 v0, 28, v110
	v_exp_f32_e32 v138, v4
	v_cvt_f32_i32_e32 v4, v125
	v_cvt_f32_i32_e32 v0, v0
	v_mul_u32_u24_e32 v19, 0x50, v11
	v_lshl_add_u64 v[94:95], s[36:37], 0, v[2:3]
	v_mul_f32_e32 v4, v13, v4
	v_mul_f32_e32 v0, v13, v0
	v_mul_f32_e32 v4, 0x3fb8aa3b, v4
	v_mul_f32_e32 v0, 0x3fb8aa3b, v0
	v_exp_f32_e32 v140, v4
	v_exp_f32_e32 v141, v0
	v_mov_b32_e32 v2, v1
	v_mov_b32_e32 v4, v1
	v_mov_b32_e32 v5, v1
	v_mov_b32_e32 v6, v1
	v_mov_b32_e32 v7, v1
	v_mov_b32_e32 v8, v1
	v_mov_b32_e32 v9, v1
	v_mov_b32_e32 v10, v1
	v_mov_b32_e32 v11, v1
	v_mov_b32_e32 v12, v1
	v_mov_b32_e32 v13, v1
	v_mov_b32_e32 v14, v1
	v_mov_b32_e32 v15, v1
	v_writelane_b32 v252, s25, 21
	v_cmp_lt_i32_e64 s[2:3], v110, v16
	v_cmp_lt_i32_e64 s[4:5], v111, v16
	v_cmp_lt_i32_e64 s[6:7], v113, v16
	v_cmp_lt_i32_e64 s[8:9], v112, v16
	v_cmp_lt_i32_e64 s[10:11], v115, v16
	v_cmp_lt_i32_e64 s[12:13], v114, v16
	v_cmp_lt_i32_e64 s[14:15], v117, v16
	v_cmp_lt_i32_e64 s[16:17], v116, v16
	v_cmp_lt_i32_e64 s[18:19], v119, v16
	v_cmp_lt_i32_e64 s[20:21], v118, v16
	v_cmp_lt_i32_e64 s[22:23], v121, v16
	v_cmp_lt_i32_e64 s[24:25], v120, v16
	v_cmp_lt_i32_e64 s[26:27], v123, v16
	v_cmp_lt_i32_e64 s[28:29], v122, v16
	v_cmp_lt_i32_e64 s[30:31], v125, v16
	v_cmp_lt_i32_e64 s[34:35], v124, v16
	v_mov_b32_e32 v0, v1
	v_add_u32_e32 v142, v17, v18
	v_add_u32_e32 v143, v17, v19
	v_mov_b64_e32 v[16:17], v[14:15]
	v_add_u32_e32 v101, 0x1200, v100
	v_mov_b32_e32 v67, v66
	v_mov_b32_e32 v92, v72
	v_mov_b32_e32 v93, v72
	v_mov_b64_e32 v[14:15], v[12:13]
	v_mov_b64_e32 v[12:13], v[10:11]
	v_mov_b64_e32 v[10:11], v[8:9]
	v_mov_b64_e32 v[8:9], v[6:7]
	v_mov_b64_e32 v[6:7], v[4:5]
	v_mov_b64_e32 v[4:5], v[2:3]
	v_mov_b64_e32 v[2:3], v[0:1]
	s_waitcnt vmcnt(0)
	s_branch .LBB0_635

; DI void ret_chain(const Params& p, int layer, int chain, char* lds) {
;     ...
;   for (int n = 0; n < 68; ++n) {
;     __syncthreads();
;     *(uint4*)(qA + lc * L4 + lp4) = pq;
;     *(uint4*)(kA + lc * L4 + lp4) = pk;
;     st8s(ks + lc * L4 + lp4, pk, __expf((float)(63 - lc) * lg));
;     *(uint4*)(vs + vc * LS + vp) = pv0;
;     *(uint4*)(vs + (vc + 32) * LS + vp) = pv1;
;     if (wm == 0) st_transp(Rt, L4, R, wm, wn, r, h);
;     if (n + 1 < 68) RET_LOAD(n + 1);
.LBB0_635:
	s_waitcnt vmcnt(18)
	v_lshlrev_b32_e32 v18, 16, v54
	v_and_b32_e32 v19, 0xffff0000, v54
	v_lshlrev_b32_e32 v20, 16, v55
	v_and_b32_e32 v21, 0xffff0000, v55
	v_pk_mul_f32 v[18:19], v[66:67], v[18:19]
	v_pk_mul_f32 v[20:21], v[66:67], v[20:21]
	v_cvt_pk_bf16_f32 v18, v18, v19
	v_cvt_pk_bf16_f32 v19, v20, v21
	v_lshlrev_b32_e32 v20, 16, v56
	v_and_b32_e32 v21, 0xffff0000, v56
	v_lshlrev_b32_e32 v22, 16, v57
	v_and_b32_e32 v23, 0xffff0000, v57
	v_pk_mul_f32 v[20:21], v[66:67], v[20:21]
	v_pk_mul_f32 v[22:23], v[66:67], v[22:23]
	v_cvt_pk_bf16_f32 v20, v20, v21
	v_cvt_pk_bf16_f32 v21, v22, v23
	s_barrier
	ds_write_b128 v99, v[50:53]
	ds_write_b128 v99, v[54:57] offset:5120
	ds_write_b128 v99, v[18:21] offset:10240
	s_waitcnt vmcnt(17)
	ds_write_b128 v100, v[58:61] offset:19456
	s_waitcnt vmcnt(16)
	ds_write_b128 v101, v[62:65] offset:19456
	s_and_saveexec_b64 s[36:37], s[0:1]
	s_cbranch_execz .LBB0_637
	v_cvt_pk_bf16_f32 v18, v2, v3
	v_cvt_pk_bf16_f32 v19, v4, v5
	v_cvt_pk_bf16_f32 v20, v6, v7
	v_cvt_pk_bf16_f32 v21, v8, v9
	v_add_u32_e32 v0, 0x9000, v109
	ds_write2_b64 v0, v[18:19], v[20:21] offset0:128 offset1:130
	v_cvt_pk_bf16_f32 v18, v10, v11
	v_cvt_pk_bf16_f32 v19, v12, v13
	v_cvt_pk_bf16_f32 v20, v14, v15
	v_cvt_pk_bf16_f32 v21, v16, v17
	ds_write2_b64 v0, v[18:19], v[20:21] offset0:132 offset1:134

; DI void pair_finalize(const Params& p, int layer, int kind, int b, int hh) {
;     ...
;   for (int j0 = 0; j0 < 68; j0 += 4) {
;     u32x4 a[4], bw[4], z[4];
; #pragma unroll
;     for (int u = 0; u < 4; ++u) {
;       const int rr = (ltid + 512 * (j0 + u)) >> 3;
;       const int row = rr < TT ? b * TT + rr : NLAT + b * LC + (rr - TT);
;       a[u] = ldg16(act + (size_t)row * AP + acol + c8 * 8);
;       bw[u] = ldg16(BW + (size_t)row * 256 + c8 * 8);
;       z[u] = ldg16(Z + (size_t)row * ZW + zcol + c8 * 8);
;     }
; #pragma unroll
;     for (int u = 0; u < 4; ++u) {
;       const int rr = (ltid + 512 * (j0 + u)) >> 3;
;       const int row = rr < TT ? b * TT + rr : NLAT + b * LC + (rr - TT);
;       float fa[8], fb[8], fz[8], o[8];
;       unpack8(a[u], fa); unpack8(bw[u], fb); unpack8(z[u], fz);
;       float sm = 0.f;
; #pragma unroll
;       for (int e = 0; e < 8; ++e) { o[e] = fa[e] + fb[e]; sm += o[e]; }
;       sm += __shfl_xor(sm, 1); sm += __shfl_xor(sm, 2); sm += __shfl_xor(sm, 4);
.LBB0_642:
	s_nop 0
	v_ashrrev_i32_e32 v10, 3, v82
	v_cmp_gt_i32_e32 vcc, s5, v10
	v_mov_b32_e32 v14, s2
	v_mov_b32_e32 v15, s41
	v_cndmask_b32_e32 v11, v14, v15, vcc
	v_add_u32_e32 v10, v11, v10
	v_ashrrev_i32_e32 v11, 31, v10
	v_lshlrev_b64 v[12:13], 9, v[10:11]
	v_mad_i64_i32 v[68:69], s[0:1], v10, s4, v[58:59]
	v_lshl_add_u64 v[12:13], v[60:61], 0, v[12:13]
	global_load_dwordx4 v[46:49], v[68:69], off
	global_load_dwordx4 v[50:53], v[12:13], off
	v_mad_i64_i32 v[10:11], s[0:1], v10, s87, v[62:63]
	global_load_dwordx4 v[54:57], v[10:11], off
	v_add_u32_e32 v10, 0x200, v82
	v_ashrrev_i32_e32 v10, 3, v10
	v_cmp_gt_i32_e32 vcc, s5, v10
	s_add_i32 s3, s3, 4
	s_cmp_gt_u32 s3, 63
	v_cndmask_b32_e32 v11, v14, v15, vcc
	v_add_u32_e32 v10, v11, v10
	v_ashrrev_i32_e32 v11, 31, v10
	v_mad_i64_i32 v[70:71], s[0:1], v10, s4, v[58:59]
	v_lshlrev_b64 v[12:13], 9, v[10:11]
	v_mad_i64_i32 v[10:11], s[0:1], v10, s87, v[62:63]
	global_load_dwordx4 v[42:45], v[10:11], off
	v_add_u32_e32 v10, 0x400, v82
	v_ashrrev_i32_e32 v10, 3, v10
	v_cmp_gt_i32_e32 vcc, s5, v10
	v_lshl_add_u64 v[12:13], v[60:61], 0, v[12:13]
	global_load_dwordx4 v[38:41], v[12:13], off
	v_cndmask_b32_e32 v11, v14, v15, vcc
	v_add_u32_e32 v10, v11, v10
	v_ashrrev_i32_e32 v11, 31, v10
	v_mad_i64_i32 v[64:65], s[0:1], v10, s4, v[58:59]
	v_lshlrev_b64 v[12:13], 9, v[10:11]
	v_mad_i64_i32 v[10:11], s[0:1], v10, s87, v[62:63]
	global_load_dwordx4 v[30:33], v[10:11], off
	v_add_u32_e32 v10, 0x600, v82
	v_ashrrev_i32_e32 v10, 3, v10
	v_cmp_gt_i32_e32 vcc, s5, v10
	global_load_dwordx4 v[34:37], v[70:71], off
	v_lshl_add_u64 v[12:13], v[60:61], 0, v[12:13]
	v_cndmask_b32_e32 v11, v14, v15, vcc
	global_load_dwordx4 v[22:25], v[64:65], off
	global_load_dwordx4 v[26:29], v[12:13], off
	v_add_u32_e32 v18, v11, v10
	v_ashrrev_i32_e32 v19, 31, v18
	v_mad_i64_i32 v[66:67], s[0:1], v18, s4, v[58:59]
	v_lshlrev_b64 v[14:15], 9, v[18:19]
	v_mad_i64_i32 v[18:19], s[0:1], v18, s87, v[62:63]
	v_lshl_add_u64 v[14:15], v[60:61], 0, v[14:15]
	global_load_dwordx4 v[10:13], v[66:67], off
	v_add_u32_e32 v82, 0x800, v82
	global_load_dwordx4 v[14:17], v[14:15], off
	s_waitcnt vmcnt(10)
	v_lshlrev_b32_e32 v72, 16, v49
	v_and_b32_e32 v73, 0xffff0000, v49
	s_waitcnt vmcnt(9)
	v_lshlrev_b32_e32 v74, 16, v53
	v_and_b32_e32 v75, 0xffff0000, v53
	v_pk_add_f32 v[74:75], v[72:73], v[74:75]
	v_lshlrev_b32_e32 v72, 16, v48
	v_and_b32_e32 v73, 0xffff0000, v48
	v_lshlrev_b32_e32 v48, 16, v52
	v_and_b32_e32 v49, 0xffff0000, v52
	s_waitcnt vmcnt(8)
	v_lshlrev_b32_e32 v52, 16, v56
	v_and_b32_e32 v53, 0xffff0000, v56
	v_pk_add_f32 v[76:77], v[72:73], v[48:49]
	v_mul_f32_e32 v48, 0xbfb8aa3b, v52
	v_mul_f32_e32 v49, 0xbfb8aa3b, v53
	v_exp_f32_e32 v48, v48
	v_exp_f32_e32 v49, v49
	v_lshlrev_b32_e32 v85, 16, v57
	v_and_b32_e32 v86, 0xffff0000, v57
	global_load_dwordx4 v[18:21], v[18:19], off
	v_pk_add_f32 v[48:49], v[48:49], 1.0 op_sel_hi:[1,0]
	s_nop 0
	v_div_scale_f32 v56, s[0:1], v49, v49, v53
	v_rcp_f32_e32 v57, v56
	s_nop 0
	v_fma_f32 v72, -v56, v57, 1.0
	v_fmac_f32_e32 v57, v72, v57
	v_div_scale_f32 v72, vcc, v53, v49, v53
	v_mul_f32_e32 v73, v72, v57
	v_fma_f32 v78, -v56, v73, v72
	v_fmac_f32_e32 v73, v78, v57
	v_fma_f32 v56, -v56, v73, v72
	v_div_fmas_f32 v56, v56, v57, v73
	v_div_fixup_f32 v49, v56, v49, v53
	v_div_scale_f32 v53, s[0:1], v48, v48, v52
	v_rcp_f32_e32 v56, v53
	s_nop 0
	v_fma_f32 v57, -v53, v56, 1.0
	v_fmac_f32_e32 v56, v57, v56
	v_div_scale_f32 v57, vcc, v52, v48, v52
	v_mul_f32_e32 v72, v57, v56
	v_fma_f32 v73, -v53, v72, v57
	v_fmac_f32_e32 v72, v73, v56
	v_fma_f32 v53, -v53, v72, v57
	v_div_fmas_f32 v53, v53, v56, v72
	v_div_fixup_f32 v48, v53, v48, v52
	v_lshlrev_b32_e32 v52, 16, v47
	v_and_b32_e32 v53, 0xffff0000, v47
	v_lshlrev_b32_e32 v56, 16, v51
	v_and_b32_e32 v57, 0xffff0000, v51
	v_lshlrev_b32_e32 v47, 16, v55
	v_and_b32_e32 v51, 0xffff0000, v55
	v_pk_add_f32 v[56:57], v[52:53], v[56:57]
	v_mul_f32_e32 v52, 0xbfb8aa3b, v47
	v_mul_f32_e32 v53, 0xbfb8aa3b, v51
	v_exp_f32_e32 v52, v52
	v_exp_f32_e32 v53, v53
	s_nop 0
	v_pk_add_f32 v[52:53], v[52:53], 1.0 op_sel_hi:[1,0]
	s_nop 0
	v_div_scale_f32 v55, s[0:1], v53, v53, v51
	v_rcp_f32_e32 v72, v55
	s_nop 0
	v_fma_f32 v73, -v55, v72, 1.0
	v_fmac_f32_e32 v72, v73, v72
	v_div_scale_f32 v73, vcc, v51, v53, v51
	v_mul_f32_e32 v78, v73, v72
	v_fma_f32 v79, -v55, v78, v73
	v_fmac_f32_e32 v78, v79, v72
	v_fma_f32 v55, -v55, v78, v73
	v_div_fmas_f32 v55, v55, v72, v78
	v_div_fixup_f32 v53, v55, v53, v51
	v_div_scale_f32 v51, s[0:1], v52, v52, v47
	v_rcp_f32_e32 v55, v51
	s_nop 0
	v_fma_f32 v72, -v51, v55, 1.0
	v_fmac_f32_e32 v55, v72, v55
	v_div_scale_f32 v72, vcc, v47, v52, v47
	v_mul_f32_e32 v73, v72, v55
	v_fma_f32 v78, -v51, v73, v72
	v_fmac_f32_e32 v73, v78, v55
	v_fma_f32 v51, -v51, v73, v72
	v_div_fmas_f32 v51, v51, v55, v73
	v_div_fixup_f32 v52, v51, v52, v47
	v_lshlrev_b32_e32 v72, 16, v46
	v_and_b32_e32 v73, 0xffff0000, v46
	v_lshlrev_b32_e32 v46, 16, v50
	v_and_b32_e32 v47, 0xffff0000, v50
	v_pk_add_f32 v[50:51], v[72:73], v[46:47]
	v_lshlrev_b32_e32 v55, 16, v54
	v_and_b32_e32 v54, 0xffff0000, v54
	v_add_f32_e32 v46, 0, v50
	v_add_f32_e32 v72, v51, v46
	v_mul_f32_e32 v46, 0xbfb8aa3b, v55
	v_mul_f32_e32 v47, 0xbfb8aa3b, v54
	v_exp_f32_e32 v46, v46
	v_exp_f32_e32 v47, v47
	s_nop 0
	v_pk_add_f32 v[46:47], v[46:47], 1.0 op_sel_hi:[1,0]
	s_nop 0
	v_div_scale_f32 v73, s[0:1], v47, v47, v54
	v_rcp_f32_e32 v78, v73
	s_nop 0
	v_fma_f32 v79, -v73, v78, 1.0
	v_fmac_f32_e32 v78, v79, v78
	v_div_scale_f32 v79, vcc, v54, v47, v54
	v_mul_f32_e32 v80, v79, v78
	v_fma_f32 v81, -v73, v80, v79
	v_fmac_f32_e32 v80, v81, v78
	v_fma_f32 v73, -v73, v80, v79
	v_div_fmas_f32 v73, v73, v78, v80
	v_div_fixup_f32 v47, v73, v47, v54
	v_div_scale_f32 v54, s[0:1], v46, v46, v55
	v_rcp_f32_e32 v73, v54
	s_nop 0
	v_fma_f32 v78, -v54, v73, 1.0
	v_fmac_f32_e32 v73, v78, v73
	v_div_scale_f32 v78, vcc, v55, v46, v55
	v_mul_f32_e32 v79, v78, v73
	v_fma_f32 v80, -v54, v79, v78
	v_fmac_f32_e32 v79, v80, v73
	v_fma_f32 v54, -v54, v79, v78
	v_div_fmas_f32 v54, v54, v73, v79
	v_div_fixup_f32 v46, v54, v46, v55
	v_add_f32_e32 v54, v56, v72
	v_add_f32_e32 v54, v57, v54
	v_add_f32_e32 v54, v76, v54
	v_add_f32_e32 v54, v77, v54
	v_add_f32_e32 v54, v74, v54
	v_add_f32_e32 v54, v75, v54
	s_nop 1
	s_waitcnt lgkmcnt(0)
; DI float siluf(float x) { return x / (1.f + __expf(-x)); }
; DI void pair_finalize(const Params& p, int layer, int kind, int b, int hh) {
;     ...
;     for (int u = 0; u < 4; ++u) {
;       const int rr = (ltid + 512 * (j0 + u)) >> 3;
;       const int row = rr < TT ? b * TT + rr : NLAT + b * LC + (rr - TT);
;       float fa[8], fb[8], fz[8], o[8];
;       unpack8(a[u], fa); unpack8(bw[u], fb); unpack8(z[u], fz);
;       float sm = 0.f;
; #pragma unroll
;       for (int e = 0; e < 8; ++e) { o[e] = fa[e] + fb[e]; sm += o[e]; }
;       sm += __shfl_xor(sm, 1); sm += __shfl_xor(sm, 2); sm += __shfl_xor(sm, 4);
;       const float mean = kind ? sm * (1.f / 64.f) : 0.f;
;       float ss = 0.f;
; #pragma unroll
;       for (int e = 0; e < 8; ++e) { o[e] -= mean; ss += o[e] * o[e]; }
;       ss += __shfl_xor(ss, 1); ss += __shfl_xor(ss, 2); ss += __shfl_xor(ss, 4);
;       const float rn = rsqrtf(ss * (1.f / 64.f) + 1e-6f);
; #pragma unroll
;       for (int e = 0; e < 8; ++e) o[e] = o[e] * rn * gg[e] * siluf(fz[e]);
	v_add_f32_dpp v54, v54, v54 quad_perm:[1,0,3,2] row_mask:0xf bank_mask:0xf
	s_nop 1
	s_waitcnt lgkmcnt(0)
	v_add_f32_dpp v54, v54, v54 quad_perm:[2,3,0,1] row_mask:0xf bank_mask:0xf
	s_nop 1
	s_waitcnt lgkmcnt(0)
	v_add_f32_dpp v54, v54, v54 row_half_mirror row_mask:0xf bank_mask:0xf
	v_mul_f32_e32 v78, 0x3c800000, v54
	v_pk_add_f32 v[72:73], v[50:51], v[78:79] op_sel_hi:[1,0] neg_lo:[0,1] neg_hi:[0,1]
	v_pk_add_f32 v[50:51], v[74:75], v[78:79] op_sel_hi:[1,0] neg_lo:[0,1] neg_hi:[0,1]
	v_mul_f32_e32 v74, 0xbfb8aa3b, v85
	v_mul_f32_e32 v75, 0xbfb8aa3b, v86
	v_exp_f32_e32 v74, v74
	v_exp_f32_e32 v75, v75
	v_pk_add_f32 v[54:55], v[76:77], v[78:79] op_sel_hi:[1,0] neg_lo:[0,1] neg_hi:[0,1]
	v_pk_mul_f32 v[80:81], v[72:73], v[72:73]
	v_pk_add_f32 v[56:57], v[56:57], v[78:79] op_sel_hi:[1,0] neg_lo:[0,1] neg_hi:[0,1]
	v_pk_add_f32 v[74:75], v[74:75], 1.0 op_sel_hi:[1,0]
	v_pk_mul_f32 v[88:89], v[56:57], v[56:57]
	v_div_scale_f32 v76, s[0:1], v75, v75, v86
	v_rcp_f32_e32 v77, v76
	v_pk_mul_f32 v[90:91], v[54:55], v[54:55]
	v_pk_mul_f32 v[78:79], v[50:51], v[50:51]
	v_fma_f32 v87, -v76, v77, 1.0
	v_fmac_f32_e32 v77, v87, v77
	v_div_scale_f32 v87, vcc, v86, v75, v86
	v_mul_f32_e32 v92, v87, v77
	v_fma_f32 v93, -v76, v92, v87
	v_fmac_f32_e32 v92, v93, v77
	v_fma_f32 v76, -v76, v92, v87
	v_div_fmas_f32 v76, v76, v77, v92
	v_div_fixup_f32 v75, v76, v75, v86
	v_div_scale_f32 v76, s[0:1], v74, v74, v85
	v_rcp_f32_e32 v77, v76
	s_waitcnt vmcnt(7)
	v_and_b32_e32 v93, 0xffff0000, v41
	v_fma_f32 v86, -v76, v77, 1.0
	v_fmac_f32_e32 v77, v86, v77
	v_div_scale_f32 v86, vcc, v85, v74, v85
	v_mul_f32_e32 v87, v86, v77
	v_fma_f32 v92, -v76, v87, v86
	v_fmac_f32_e32 v87, v92, v77
	v_fma_f32 v76, -v76, v87, v86
	v_div_fmas_f32 v76, v76, v77, v87
	v_div_fixup_f32 v74, v76, v74, v85
	s_waitcnt vmcnt(5)
	v_lshlrev_b32_e32 v76, 16, v37
	v_and_b32_e32 v77, 0xffff0000, v37
	v_lshlrev_b32_e32 v92, 16, v41
	v_pk_add_f32 v[92:93], v[76:77], v[92:93]
	v_lshlrev_b32_e32 v76, 16, v36
	v_and_b32_e32 v77, 0xffff0000, v36
	v_lshlrev_b32_e32 v36, 16, v40
	v_and_b32_e32 v37, 0xffff0000, v40
	v_lshlrev_b32_e32 v40, 16, v44
	v_and_b32_e32 v41, 0xffff0000, v44
	v_lshlrev_b32_e32 v85, 16, v45
	v_and_b32_e32 v86, 0xffff0000, v45
	v_pk_add_f32 v[44:45], v[76:77], v[36:37]
	v_mul_f32_e32 v36, 0xbfb8aa3b, v40
	v_mul_f32_e32 v37, 0xbfb8aa3b, v41
	v_exp_f32_e32 v36, v36
	v_exp_f32_e32 v37, v37
	s_nop 0
	v_pk_add_f32 v[36:37], v[36:37], 1.0 op_sel_hi:[1,0]
	s_nop 0
	v_div_scale_f32 v76, s[0:1], v37, v37, v41
	v_rcp_f32_e32 v77, v76
	s_nop 0
	v_fma_f32 v87, -v76, v77, 1.0
	v_fmac_f32_e32 v77, v87, v77
	v_div_scale_f32 v87, vcc, v41, v37, v41
	v_mul_f32_e32 v94, v87, v77
	v_fma_f32 v95, -v76, v94, v87
	v_fmac_f32_e32 v94, v95, v77
	v_fma_f32 v76, -v76, v94, v87
	v_div_fmas_f32 v76, v76, v77, v94
	v_div_fixup_f32 v37, v76, v37, v41
	v_div_scale_f32 v41, s[0:1], v36, v36, v40
	v_rcp_f32_e32 v76, v41
	s_nop 0
	v_fma_f32 v77, -v41, v76, 1.0
	v_fmac_f32_e32 v76, v77, v76
	v_div_scale_f32 v77, vcc, v40, v36, v40
	v_mul_f32_e32 v87, v77, v76
	v_fma_f32 v94, -v41, v87, v77
	v_fmac_f32_e32 v87, v94, v76
	v_fma_f32 v41, -v41, v87, v77
	v_div_fmas_f32 v41, v41, v76, v87
	v_div_fixup_f32 v36, v41, v36, v40
	v_lshlrev_b32_e32 v40, 16, v35
	v_and_b32_e32 v41, 0xffff0000, v35
	v_lshlrev_b32_e32 v76, 16, v39
	v_and_b32_e32 v77, 0xffff0000, v39
	v_lshlrev_b32_e32 v35, 16, v43
	v_and_b32_e32 v39, 0xffff0000, v43
	v_pk_add_f32 v[76:77], v[40:41], v[76:77]
	v_mul_f32_e32 v40, 0xbfb8aa3b, v35
	v_mul_f32_e32 v41, 0xbfb8aa3b, v39
	v_exp_f32_e32 v40, v40
	v_exp_f32_e32 v41, v41
	s_nop 0
	v_pk_add_f32 v[40:41], v[40:41], 1.0 op_sel_hi:[1,0]
	s_nop 0
	v_div_scale_f32 v43, s[0:1], v41, v41, v39
	v_rcp_f32_e32 v87, v43
	s_nop 0
	v_fma_f32 v94, -v43, v87, 1.0
	v_fmac_f32_e32 v87, v94, v87
	v_div_scale_f32 v94, vcc, v39, v41, v39
	v_mul_f32_e32 v95, v94, v87
	v_fma_f32 v96, -v43, v95, v94
	v_fmac_f32_e32 v95, v96, v87
	v_fma_f32 v43, -v43, v95, v94
	v_div_fmas_f32 v43, v43, v87, v95
	v_div_fixup_f32 v41, v43, v41, v39
	v_div_scale_f32 v39, s[0:1], v40, v40, v35
	v_rcp_f32_e32 v43, v39
	s_nop 0
	v_fma_f32 v87, -v39, v43, 1.0
	v_fmac_f32_e32 v43, v87, v43
	v_div_scale_f32 v87, vcc, v35, v40, v35
	v_mul_f32_e32 v94, v87, v43
	v_fma_f32 v95, -v39, v94, v87
	v_fmac_f32_e32 v94, v95, v43
	v_fma_f32 v39, -v39, v94, v87
	v_div_fmas_f32 v39, v39, v43, v94
	v_div_fixup_f32 v40, v39, v40, v35
	v_lshlrev_b32_e32 v94, 16, v34
	v_and_b32_e32 v95, 0xffff0000, v34
	v_lshlrev_b32_e32 v34, 16, v38
	v_and_b32_e32 v35, 0xffff0000, v38
	v_pk_add_f32 v[38:39], v[94:95], v[34:35]
	v_lshlrev_b32_e32 v43, 16, v42
	v_and_b32_e32 v42, 0xffff0000, v42
	v_add_f32_e32 v34, 0, v38
	v_add_f32_e32 v87, v39, v34
	v_mul_f32_e32 v34, 0xbfb8aa3b, v43
	v_mul_f32_e32 v35, 0xbfb8aa3b, v42
	v_exp_f32_e32 v34, v34
	v_exp_f32_e32 v35, v35
	s_nop 0
	v_pk_add_f32 v[34:35], v[34:35], 1.0 op_sel_hi:[1,0]
	s_nop 0
	v_div_scale_f32 v94, s[0:1], v35, v35, v42
	v_rcp_f32_e32 v95, v94
	s_nop 0
	v_fma_f32 v96, -v94, v95, 1.0
	v_fmac_f32_e32 v95, v96, v95
	v_div_scale_f32 v96, vcc, v42, v35, v42
	v_mul_f32_e32 v97, v96, v95
	v_fma_f32 v98, -v94, v97, v96
	v_fmac_f32_e32 v97, v98, v95
	v_fma_f32 v94, -v94, v97, v96
	v_div_fmas_f32 v94, v94, v95, v97
	v_div_fixup_f32 v35, v94, v35, v42
	v_div_scale_f32 v42, s[0:1], v34, v34, v43
	v_rcp_f32_e32 v94, v42
	s_nop 0
	v_fma_f32 v95, -v42, v94, 1.0
	v_fmac_f32_e32 v94, v95, v94
	v_div_scale_f32 v95, vcc, v43, v34, v43
	v_mul_f32_e32 v96, v95, v94
	v_fma_f32 v97, -v42, v96, v95
	v_fmac_f32_e32 v96, v97, v94
	v_fma_f32 v42, -v42, v96, v95
	v_div_fmas_f32 v42, v42, v94, v96
	v_div_fixup_f32 v34, v42, v34, v43
	v_add_f32_e32 v42, v76, v87
	v_add_f32_e32 v42, v77, v42
	v_add_f32_e32 v42, v44, v42
	v_add_f32_e32 v42, v45, v42
	v_add_f32_e32 v42, v92, v42
	v_add_f32_e32 v42, v93, v42
	ds_bpermute_b32 v43, v0, v42
	v_mov_b32_e32 v97, v80
	s_waitcnt lgkmcnt(0)
; DI float siluf(float x) { return x / (1.f + __expf(-x)); }
; DI void pair_finalize(const Params& p, int layer, int kind, int b, int hh) {
;     ...
;     for (int u = 0; u < 4; ++u) {
;       const int rr = (ltid + 512 * (j0 + u)) >> 3;
;       const int row = rr < TT ? b * TT + rr : NLAT + b * LC + (rr - TT);
;       float fa[8], fb[8], fz[8], o[8];
;       unpack8(a[u], fa); unpack8(bw[u], fb); unpack8(z[u], fz);
;       float sm = 0.f;
; #pragma unroll
;       for (int e = 0; e < 8; ++e) { o[e] = fa[e] + fb[e]; sm += o[e]; }
;       sm += __shfl_xor(sm, 1); sm += __shfl_xor(sm, 2); sm += __shfl_xor(sm, 4);
;       const float mean = kind ? sm * (1.f / 64.f) : 0.f;
;       float ss = 0.f;
; #pragma unroll
;       for (int e = 0; e < 8; ++e) { o[e] -= mean; ss += o[e] * o[e]; }
;       ss += __shfl_xor(ss, 1); ss += __shfl_xor(ss, 2); ss += __shfl_xor(ss, 4);
;       const float rn = rsqrtf(ss * (1.f / 64.f) + 1e-6f);
; #pragma unroll
;       for (int e = 0; e < 8; ++e) o[e] = o[e] * rn * gg[e] * siluf(fz[e]);
;       *(u32x4*)(act + (size_t)row * AP + acol + c8 * 8) = pack8(o);
	v_add_f32_e32 v42, v42, v43
	s_nop 1
	s_waitcnt lgkmcnt(0)
	v_add_f32_dpp v42, v42, v42 quad_perm:[2,3,0,1] row_mask:0xf bank_mask:0xf
	s_nop 1
	s_waitcnt lgkmcnt(0)
	v_add_f32_dpp v42, v42, v42 row_half_mirror row_mask:0xf bank_mask:0xf
	v_mul_f32_e32 v94, 0x3c800000, v42
	v_pk_add_f32 v[42:43], v[38:39], v[94:95] op_sel_hi:[1,0] neg_lo:[0,1] neg_hi:[0,1]
	v_pk_add_f32 v[76:77], v[76:77], v[94:95] op_sel_hi:[1,0] neg_lo:[0,1] neg_hi:[0,1]
	v_pk_mul_f32 v[38:39], v[42:43], v[42:43]
	v_pk_add_f32 v[44:45], v[44:45], v[94:95] op_sel_hi:[1,0] neg_lo:[0,1] neg_hi:[0,1]
	v_mov_b32_e32 v96, v38
	v_mov_b32_e32 v80, v39
	v_pk_add_f32 v[80:81], v[96:97], v[80:81]
	v_pk_mul_f32 v[96:97], v[76:77], v[76:77]
	v_pk_add_f32 v[38:39], v[92:93], v[94:95] op_sel_hi:[1,0] neg_lo:[0,1] neg_hi:[0,1]
	v_mov_b32_e32 v94, v96
	v_mov_b32_e32 v95, v88
	v_pk_mul_f32 v[98:99], v[44:45], v[44:45]
	v_pk_add_f32 v[80:81], v[94:95], v[80:81]
	v_mov_b32_e32 v88, v97
	v_pk_add_f32 v[80:81], v[88:89], v[80:81]
	v_mov_b32_e32 v88, v98
	v_mov_b32_e32 v89, v90
	v_pk_mul_f32 v[92:93], v[38:39], v[38:39]
	v_pk_add_f32 v[80:81], v[88:89], v[80:81]
	v_mov_b32_e32 v90, v99
	v_pk_add_f32 v[80:81], v[90:91], v[80:81]
	v_mov_b32_e32 v88, v92
	v_mov_b32_e32 v89, v78
	v_pk_add_f32 v[80:81], v[88:89], v[80:81]
	v_mov_b32_e32 v78, v93
	v_pk_add_f32 v[78:79], v[78:79], v[80:81]
	s_nop 1
	v_add_f32_dpp v78, v78, v78 quad_perm:[1,0,3,2] row_mask:0xf bank_mask:0xf
	s_waitcnt lgkmcnt(0)
	v_add_f32_dpp v79, v79, v79 quad_perm:[1,0,3,2] row_mask:0xf bank_mask:0xf
	s_nop 1
	v_add_f32_dpp v78, v78, v78 quad_perm:[2,3,0,1] row_mask:0xf bank_mask:0xf
	s_waitcnt lgkmcnt(0)
	v_add_f32_dpp v79, v79, v79 quad_perm:[2,3,0,1] row_mask:0xf bank_mask:0xf
	s_nop 1
	v_add_f32_dpp v78, v78, v78 row_half_mirror row_mask:0xf bank_mask:0xf
	s_waitcnt lgkmcnt(0)
	v_add_f32_dpp v79, v79, v79 row_half_mirror row_mask:0xf bank_mask:0xf
	v_mov_b64_e32 v[80:81], s[8:9]
	v_pk_fma_f32 v[78:79], v[78:79], s[10:11], v[80:81] op_sel_hi:[1,0,0]
	s_nop 0
	v_mul_f32_e32 v87, 0x4b800000, v79
	v_cmp_gt_f32_e64 s[0:1], s6, v79
	v_cmp_gt_f32_e32 vcc, s6, v78
	s_nop 0
	v_cndmask_b32_e64 v79, v79, v87, s[0:1]
	v_rsq_f32_e32 v79, v79
	s_nop 0
	v_mul_f32_e32 v87, 0x45800000, v79
	v_cndmask_b32_e64 v88, v79, v87, s[0:1]
	v_pk_mul_f32 v[72:73], v[72:73], v[88:89] op_sel_hi:[1,0]
	v_pk_mul_f32 v[56:57], v[56:57], v[88:89] op_sel_hi:[1,0]
	v_pk_mul_f32 v[54:55], v[54:55], v[88:89] op_sel_hi:[1,0]
	v_pk_mul_f32 v[50:51], v[50:51], v[88:89] op_sel_hi:[1,0]
	v_pk_mul_f32 v[72:73], v[6:7], v[72:73]
	v_pk_mul_f32 v[56:57], v[8:9], v[56:57]
	v_pk_mul_f32 v[54:55], v[2:3], v[54:55]
	v_pk_mul_f32 v[50:51], v[4:5], v[50:51]
	v_pk_mul_f32 v[46:47], v[46:47], v[72:73]
	v_pk_mul_f32 v[52:53], v[52:53], v[56:57]
	v_pk_mul_f32 v[48:49], v[48:49], v[54:55]
	v_pk_mul_f32 v[50:51], v[74:75], v[50:51]
	v_cvt_pk_bf16_f32 v46, v46, v47
	v_cvt_pk_bf16_f32 v47, v52, v53
	v_cvt_pk_bf16_f32 v48, v48, v49
	v_cvt_pk_bf16_f32 v49, v50, v51
	global_store_dwordx4 v[68:69], v[46:49], off
	s_waitcnt vmcnt(1)
	v_lshlrev_b32_e32 v56, 16, v21
	v_and_b32_e32 v57, 0xffff0000, v21
	v_mul_f32_e32 v46, 0x4b800000, v78
	v_cndmask_b32_e32 v46, v78, v46, vcc
	v_rsq_f32_e32 v46, v46
	v_lshlrev_b32_e32 v21, 16, v20
	v_and_b32_e32 v20, 0xffff0000, v20
	v_mul_f32_e32 v47, 0x45800000, v46
	v_cndmask_b32_e32 v46, v46, v47, vcc
	v_pk_mul_f32 v[42:43], v[42:43], v[46:47] op_sel_hi:[1,0]
	v_pk_mul_f32 v[38:39], v[38:39], v[46:47] op_sel_hi:[1,0]
	v_pk_mul_f32 v[42:43], v[6:7], v[42:43]
	v_pk_mul_f32 v[38:39], v[4:5], v[38:39]
	v_pk_mul_f32 v[34:35], v[34:35], v[42:43]
	v_pk_mul_f32 v[42:43], v[76:77], v[46:47] op_sel_hi:[1,0]
	v_cvt_pk_bf16_f32 v34, v34, v35
	v_pk_mul_f32 v[42:43], v[8:9], v[42:43]
	s_nop 0
	v_pk_mul_f32 v[40:41], v[40:41], v[42:43]
	v_pk_mul_f32 v[42:43], v[44:45], v[46:47] op_sel_hi:[1,0]
	v_cvt_pk_bf16_f32 v35, v40, v41
	v_pk_mul_f32 v[42:43], v[2:3], v[42:43]
	s_nop 0
	v_pk_mul_f32 v[36:37], v[36:37], v[42:43]
	v_mul_f32_e32 v42, 0xbfb8aa3b, v85
	v_mul_f32_e32 v43, 0xbfb8aa3b, v86
	v_exp_f32_e32 v42, v42
	v_exp_f32_e32 v43, v43
	v_cvt_pk_bf16_f32 v36, v36, v37
	v_pk_add_f32 v[42:43], v[42:43], 1.0 op_sel_hi:[1,0]
	s_nop 0
	v_div_scale_f32 v44, s[0:1], v43, v43, v86
	v_rcp_f32_e32 v45, v44
	s_nop 0
	v_fma_f32 v46, -v44, v45, 1.0
	v_fmac_f32_e32 v45, v46, v45
	v_div_scale_f32 v46, vcc, v86, v43, v86
	v_mul_f32_e32 v47, v46, v45
	v_fma_f32 v48, -v44, v47, v46
	v_fmac_f32_e32 v47, v48, v45
	v_fma_f32 v44, -v44, v47, v46
	v_div_fmas_f32 v44, v44, v45, v47
	v_div_fixup_f32 v43, v44, v43, v86
	v_div_scale_f32 v44, s[0:1], v42, v42, v85
	v_rcp_f32_e32 v45, v44
	s_nop 0
	v_fma_f32 v46, -v44, v45, 1.0
	v_fmac_f32_e32 v45, v46, v45
	v_div_scale_f32 v46, vcc, v85, v42, v85
	v_mul_f32_e32 v47, v46, v45
	v_fma_f32 v48, -v44, v47, v46
	v_fmac_f32_e32 v47, v48, v45
	v_fma_f32 v44, -v44, v47, v46
	v_div_fmas_f32 v44, v44, v45, v47
	v_div_fixup_f32 v42, v44, v42, v85
	v_pk_mul_f32 v[38:39], v[42:43], v[38:39]
	v_lshlrev_b32_e32 v46, 16, v33
	v_cvt_pk_bf16_f32 v37, v38, v39
	global_store_dwordx4 v[70:71], v[34:37], off
	v_and_b32_e32 v47, 0xffff0000, v33
	v_mul_f32_e32 v44, 0xbfb8aa3b, v46
	v_lshlrev_b32_e32 v34, 16, v25
	v_and_b32_e32 v35, 0xffff0000, v25
	v_lshlrev_b32_e32 v36, 16, v29
	v_and_b32_e32 v37, 0xffff0000, v29
	v_pk_add_f32 v[34:35], v[34:35], v[36:37]
	v_lshlrev_b32_e32 v36, 16, v24
	v_and_b32_e32 v37, 0xffff0000, v24
	v_lshlrev_b32_e32 v24, 16, v28
	v_and_b32_e32 v25, 0xffff0000, v28
	v_lshlrev_b32_e32 v28, 16, v32
	v_and_b32_e32 v29, 0xffff0000, v32
	v_pk_add_f32 v[32:33], v[36:37], v[24:25]
	v_mul_f32_e32 v24, 0xbfb8aa3b, v28
	v_mul_f32_e32 v25, 0xbfb8aa3b, v29
; DI float siluf(float x) { return x / (1.f + __expf(-x)); }
; DI void pair_finalize(const Params& p, int layer, int kind, int b, int hh) {
;     ...
;     for (int u = 0; u < 4; ++u) {
;       const int rr = (ltid + 512 * (j0 + u)) >> 3;
;       const int row = rr < TT ? b * TT + rr : NLAT + b * LC + (rr - TT);
;       float fa[8], fb[8], fz[8], o[8];
;       unpack8(a[u], fa); unpack8(bw[u], fb); unpack8(z[u], fz);
;       float sm = 0.f;
; #pragma unroll
;       for (int e = 0; e < 8; ++e) { o[e] = fa[e] + fb[e]; sm += o[e]; }
;       sm += __shfl_xor(sm, 1); sm += __shfl_xor(sm, 2); sm += __shfl_xor(sm, 4);
;       const float mean = kind ? sm * (1.f / 64.f) : 0.f;
;       float ss = 0.f;
; #pragma unroll
;       for (int e = 0; e < 8; ++e) { o[e] -= mean; ss += o[e] * o[e]; }
;       ss += __shfl_xor(ss, 1); ss += __shfl_xor(ss, 2); ss += __shfl_xor(ss, 4);
;       const float rn = rsqrtf(ss * (1.f / 64.f) + 1e-6f);
; #pragma unroll
;       for (int e = 0; e < 8; ++e) o[e] = o[e] * rn * gg[e] * siluf(fz[e]);
	v_exp_f32_e32 v24, v24
	v_exp_f32_e32 v25, v25
	v_mul_f32_e32 v45, 0xbfb8aa3b, v47
	v_exp_f32_e32 v44, v44
	v_exp_f32_e32 v45, v45
	v_pk_add_f32 v[24:25], v[24:25], 1.0 op_sel_hi:[1,0]
	v_pk_add_f32 v[44:45], v[44:45], 1.0 op_sel_hi:[1,0]
	v_div_scale_f32 v36, s[0:1], v25, v25, v29
	v_rcp_f32_e32 v37, v36
	v_div_scale_f32 v48, s[0:1], v45, v45, v47
	v_rcp_f32_e32 v49, v48
	v_fma_f32 v38, -v36, v37, 1.0
	v_fmac_f32_e32 v37, v38, v37
	v_div_scale_f32 v38, vcc, v29, v25, v29
	v_mul_f32_e32 v39, v38, v37
	v_fma_f32 v40, -v36, v39, v38
	v_fmac_f32_e32 v39, v40, v37
	v_fma_f32 v36, -v36, v39, v38
	v_div_fmas_f32 v36, v36, v37, v39
	v_div_fixup_f32 v25, v36, v25, v29
	v_div_scale_f32 v29, s[0:1], v24, v24, v28
	v_rcp_f32_e32 v36, v29
	v_fma_f32 v50, -v48, v49, 1.0
	v_fmac_f32_e32 v49, v50, v49
	v_fma_f32 v37, -v29, v36, 1.0
	v_fmac_f32_e32 v36, v37, v36
	v_div_scale_f32 v37, vcc, v28, v24, v28
	v_mul_f32_e32 v38, v37, v36
	v_fma_f32 v39, -v29, v38, v37
	v_fmac_f32_e32 v38, v39, v36
	v_fma_f32 v29, -v29, v38, v37
	v_div_fmas_f32 v29, v29, v36, v38
	v_div_fixup_f32 v24, v29, v24, v28
	v_lshlrev_b32_e32 v28, 16, v23
	v_and_b32_e32 v29, 0xffff0000, v23
	v_lshlrev_b32_e32 v36, 16, v27
	v_and_b32_e32 v37, 0xffff0000, v27
	v_lshlrev_b32_e32 v23, 16, v31
	v_and_b32_e32 v27, 0xffff0000, v31
	v_pk_add_f32 v[36:37], v[28:29], v[36:37]
	v_mul_f32_e32 v28, 0xbfb8aa3b, v23
	v_mul_f32_e32 v29, 0xbfb8aa3b, v27
	v_exp_f32_e32 v28, v28
	v_exp_f32_e32 v29, v29
	s_nop 0
	v_pk_add_f32 v[28:29], v[28:29], 1.0 op_sel_hi:[1,0]
	s_nop 0
	v_div_scale_f32 v31, s[0:1], v29, v29, v27
	v_rcp_f32_e32 v38, v31
	s_nop 0
	v_fma_f32 v39, -v31, v38, 1.0
	v_fmac_f32_e32 v38, v39, v38
	v_div_scale_f32 v39, vcc, v27, v29, v27
	v_mul_f32_e32 v40, v39, v38
	v_fma_f32 v41, -v31, v40, v39
	v_fmac_f32_e32 v40, v41, v38
	v_fma_f32 v31, -v31, v40, v39
	v_div_fmas_f32 v31, v31, v38, v40
	v_div_fixup_f32 v29, v31, v29, v27
	v_div_scale_f32 v27, s[0:1], v28, v28, v23
	v_rcp_f32_e32 v31, v27
	s_nop 0
	v_fma_f32 v38, -v27, v31, 1.0
	v_fmac_f32_e32 v31, v38, v31
	v_div_scale_f32 v38, vcc, v23, v28, v23
	v_mul_f32_e32 v39, v38, v31
	v_fma_f32 v40, -v27, v39, v38
	v_fmac_f32_e32 v39, v40, v31
	v_fma_f32 v27, -v27, v39, v38
	v_div_fmas_f32 v27, v27, v31, v39
	v_div_fixup_f32 v28, v27, v28, v23
	v_lshlrev_b32_e32 v38, 16, v22
	v_and_b32_e32 v39, 0xffff0000, v22
	v_lshlrev_b32_e32 v22, 16, v26
	v_and_b32_e32 v23, 0xffff0000, v26
	v_pk_add_f32 v[22:23], v[38:39], v[22:23]
	v_lshlrev_b32_e32 v31, 16, v30
	v_and_b32_e32 v30, 0xffff0000, v30
	v_add_f32_e32 v26, 0, v22
	v_add_f32_e32 v38, v23, v26
	v_mul_f32_e32 v26, 0xbfb8aa3b, v31
	v_mul_f32_e32 v27, 0xbfb8aa3b, v30
	v_exp_f32_e32 v26, v26
	v_exp_f32_e32 v27, v27
	s_nop 0
	v_pk_add_f32 v[26:27], v[26:27], 1.0 op_sel_hi:[1,0]
	s_nop 0
	v_div_scale_f32 v39, s[0:1], v27, v27, v30
	v_rcp_f32_e32 v40, v39
	s_nop 0
	v_fma_f32 v41, -v39, v40, 1.0
	v_fmac_f32_e32 v40, v41, v40
	v_div_scale_f32 v41, vcc, v30, v27, v30
	v_mul_f32_e32 v42, v41, v40
	v_fma_f32 v43, -v39, v42, v41
	v_fmac_f32_e32 v42, v43, v40
	v_fma_f32 v39, -v39, v42, v41
	v_div_fmas_f32 v39, v39, v40, v42
	v_div_fixup_f32 v27, v39, v27, v30
	v_div_scale_f32 v30, s[0:1], v26, v26, v31
	v_rcp_f32_e32 v39, v30
	s_nop 0
	v_fma_f32 v40, -v30, v39, 1.0
	v_fmac_f32_e32 v39, v40, v39
	v_div_scale_f32 v40, vcc, v31, v26, v31
	v_mul_f32_e32 v41, v40, v39
	v_fma_f32 v42, -v30, v41, v40
	v_fmac_f32_e32 v41, v42, v39
	v_fma_f32 v30, -v30, v41, v40
	v_div_fmas_f32 v30, v30, v39, v41
	v_div_scale_f32 v50, vcc, v47, v45, v47
	v_mul_f32_e32 v51, v50, v49
	v_fma_f32 v52, -v48, v51, v50
	v_fmac_f32_e32 v51, v52, v49
	v_fma_f32 v48, -v48, v51, v50
	v_div_fmas_f32 v48, v48, v49, v51
	v_div_fixup_f32 v45, v48, v45, v47
	v_div_scale_f32 v47, s[0:1], v44, v44, v46
	v_rcp_f32_e32 v48, v47
	v_div_fixup_f32 v26, v30, v26, v31
	v_add_f32_e32 v30, v36, v38
	v_add_f32_e32 v30, v37, v30
	v_fma_f32 v49, -v47, v48, 1.0
	v_fmac_f32_e32 v48, v49, v48
	v_div_scale_f32 v49, vcc, v46, v44, v46
	v_mul_f32_e32 v50, v49, v48
	v_fma_f32 v51, -v47, v50, v49
	v_fmac_f32_e32 v50, v51, v48
	v_fma_f32 v47, -v47, v50, v49
	v_div_fmas_f32 v47, v47, v48, v50
	v_div_fixup_f32 v44, v47, v44, v46
	v_lshlrev_b32_e32 v46, 16, v13
	v_and_b32_e32 v47, 0xffff0000, v13
	v_lshlrev_b32_e32 v48, 16, v17
	v_and_b32_e32 v49, 0xffff0000, v17
	v_pk_add_f32 v[46:47], v[46:47], v[48:49]
	v_lshlrev_b32_e32 v48, 16, v12
	v_and_b32_e32 v49, 0xffff0000, v12
	v_lshlrev_b32_e32 v12, 16, v16
	v_and_b32_e32 v13, 0xffff0000, v16
	v_mul_f32_e32 v16, 0xbfb8aa3b, v21
	v_mul_f32_e32 v17, 0xbfb8aa3b, v20
	v_exp_f32_e32 v16, v16
	v_exp_f32_e32 v17, v17
	v_pk_add_f32 v[12:13], v[48:49], v[12:13]
	v_add_f32_e32 v30, v32, v30
	v_add_f32_e32 v30, v33, v30
	v_pk_add_f32 v[16:17], v[16:17], 1.0 op_sel_hi:[1,0]
	v_add_f32_e32 v30, v34, v30
	v_div_scale_f32 v48, s[0:1], v17, v17, v20
	v_rcp_f32_e32 v49, v48
	v_add_f32_e32 v30, v35, v30
	ds_bpermute_b32 v31, v0, v30
	v_fma_f32 v50, -v48, v49, 1.0
	v_fmac_f32_e32 v49, v50, v49
	v_div_scale_f32 v50, vcc, v20, v17, v20
	v_mul_f32_e32 v51, v50, v49
	v_fma_f32 v52, -v48, v51, v50
	v_fmac_f32_e32 v51, v52, v49
	v_fma_f32 v48, -v48, v51, v50
	v_div_fmas_f32 v48, v48, v49, v51
	v_div_fixup_f32 v17, v48, v17, v20
	v_div_scale_f32 v20, s[0:1], v16, v16, v21
	v_rcp_f32_e32 v48, v20
	s_waitcnt lgkmcnt(0)
; DI float siluf(float x) { return x / (1.f + __expf(-x)); }
; DI void pair_finalize(const Params& p, int layer, int kind, int b, int hh) {
;     ...
;     for (int u = 0; u < 4; ++u) {
;       const int rr = (ltid + 512 * (j0 + u)) >> 3;
;       const int row = rr < TT ? b * TT + rr : NLAT + b * LC + (rr - TT);
;       float fa[8], fb[8], fz[8], o[8];
;       unpack8(a[u], fa); unpack8(bw[u], fb); unpack8(z[u], fz);
;       float sm = 0.f;
; #pragma unroll
;       for (int e = 0; e < 8; ++e) { o[e] = fa[e] + fb[e]; sm += o[e]; }
;       sm += __shfl_xor(sm, 1); sm += __shfl_xor(sm, 2); sm += __shfl_xor(sm, 4);
;       const float mean = kind ? sm * (1.f / 64.f) : 0.f;
;       float ss = 0.f;
; #pragma unroll
;       for (int e = 0; e < 8; ++e) { o[e] -= mean; ss += o[e] * o[e]; }
;       ss += __shfl_xor(ss, 1); ss += __shfl_xor(ss, 2); ss += __shfl_xor(ss, 4);
;       const float rn = rsqrtf(ss * (1.f / 64.f) + 1e-6f);
; #pragma unroll
;       for (int e = 0; e < 8; ++e) o[e] = o[e] * rn * gg[e] * siluf(fz[e]);
	v_add_f32_e32 v30, v30, v31
	ds_bpermute_b32 v31, v83, v30
	v_fma_f32 v49, -v20, v48, 1.0
	v_fmac_f32_e32 v48, v49, v48
	v_div_scale_f32 v49, vcc, v21, v16, v21
	v_mul_f32_e32 v50, v49, v48
	v_fma_f32 v51, -v20, v50, v49
	v_fmac_f32_e32 v50, v51, v48
	v_fma_f32 v20, -v20, v50, v49
	v_div_fmas_f32 v20, v20, v48, v50
	v_div_fixup_f32 v16, v20, v16, v21
	v_lshlrev_b32_e32 v20, 16, v11
	v_and_b32_e32 v21, 0xffff0000, v11
	v_lshlrev_b32_e32 v11, 16, v19
	v_lshlrev_b32_e32 v48, 16, v15
	v_and_b32_e32 v49, 0xffff0000, v15
	v_and_b32_e32 v15, 0xffff0000, v19
	v_mul_f32_e32 v19, 0xbfb8aa3b, v11
	v_pk_add_f32 v[20:21], v[20:21], v[48:49]
	v_exp_f32_e32 v48, v19
	v_mul_f32_e32 v19, 0xbfb8aa3b, v15
	v_exp_f32_e32 v49, v19
	s_waitcnt lgkmcnt(0)
	v_add_f32_e32 v30, v30, v31
	ds_bpermute_b32 v31, v84, v30
	v_pk_add_f32 v[48:49], v[48:49], 1.0 op_sel_hi:[1,0]
	s_nop 0
	v_div_scale_f32 v19, s[0:1], v49, v49, v15
	v_rcp_f32_e32 v50, v19
	s_waitcnt lgkmcnt(0)
	v_add_f32_e32 v30, v30, v31
	v_mul_f32_e32 v30, 0x3c800000, v30
	v_pk_add_f32 v[22:23], v[22:23], v[30:31] op_sel_hi:[1,0] neg_lo:[0,1] neg_hi:[0,1]
	v_fma_f32 v51, -v19, v50, 1.0
	v_fmac_f32_e32 v50, v51, v50
	v_div_scale_f32 v51, vcc, v15, v49, v15
	v_mul_f32_e32 v52, v51, v50
	v_fma_f32 v53, -v19, v52, v51
	v_fmac_f32_e32 v52, v53, v50
	v_fma_f32 v19, -v19, v52, v51
	v_div_fmas_f32 v19, v19, v50, v52
	v_div_fixup_f32 v49, v19, v49, v15
	v_div_scale_f32 v15, s[0:1], v48, v48, v11
	v_rcp_f32_e32 v19, v15
	v_pk_mul_f32 v[38:39], v[22:23], v[22:23]
	v_pk_add_f32 v[36:37], v[36:37], v[30:31] op_sel_hi:[1,0] neg_lo:[0,1] neg_hi:[0,1]
	v_pk_add_f32 v[32:33], v[32:33], v[30:31] op_sel_hi:[1,0] neg_lo:[0,1] neg_hi:[0,1]
	v_fma_f32 v50, -v15, v19, 1.0
	v_fmac_f32_e32 v19, v50, v19
	v_div_scale_f32 v50, vcc, v11, v48, v11
	v_mul_f32_e32 v51, v50, v19
	v_fma_f32 v52, -v15, v51, v50
	v_fmac_f32_e32 v51, v52, v19
	v_fma_f32 v15, -v15, v51, v50
	v_div_fmas_f32 v15, v15, v19, v51
	v_div_fixup_f32 v48, v15, v48, v11
	v_lshlrev_b32_e32 v50, 16, v10
	v_and_b32_e32 v51, 0xffff0000, v10
	v_lshlrev_b32_e32 v10, 16, v14
	v_and_b32_e32 v11, 0xffff0000, v14
	v_pk_add_f32 v[10:11], v[50:51], v[10:11]
	v_lshlrev_b32_e32 v19, 16, v18
	v_and_b32_e32 v18, 0xffff0000, v18
	v_add_f32_e32 v14, 0, v10
	v_add_f32_e32 v50, v11, v14
	v_mul_f32_e32 v14, 0xbfb8aa3b, v19
	v_mul_f32_e32 v15, 0xbfb8aa3b, v18
	v_exp_f32_e32 v14, v14
	v_exp_f32_e32 v15, v15
	v_pk_mul_f32 v[40:41], v[36:37], v[36:37]
	v_pk_mul_f32 v[42:43], v[32:33], v[32:33]
	v_pk_add_f32 v[30:31], v[34:35], v[30:31] op_sel_hi:[1,0] neg_lo:[0,1] neg_hi:[0,1]
	v_pk_add_f32 v[14:15], v[14:15], 1.0 op_sel_hi:[1,0]
	v_pk_mul_f32 v[34:35], v[30:31], v[30:31]
	v_div_scale_f32 v51, s[0:1], v15, v15, v18
	v_rcp_f32_e32 v52, v51
	s_nop 0
	v_fma_f32 v53, -v51, v52, 1.0
	v_fmac_f32_e32 v52, v53, v52
	v_div_scale_f32 v53, vcc, v18, v15, v18
	v_mul_f32_e32 v54, v53, v52
	v_fma_f32 v55, -v51, v54, v53
	v_fmac_f32_e32 v54, v55, v52
	v_fma_f32 v51, -v51, v54, v53
	v_div_fmas_f32 v51, v51, v52, v54
	v_div_fixup_f32 v15, v51, v15, v18
	v_div_scale_f32 v18, s[0:1], v14, v14, v19
	v_rcp_f32_e32 v51, v18
	v_mov_b32_e32 v55, v40
	v_fma_f32 v52, -v18, v51, 1.0
	v_fmac_f32_e32 v51, v52, v51
	v_div_scale_f32 v52, vcc, v19, v14, v19
	v_mul_f32_e32 v53, v52, v51
	v_fma_f32 v54, -v18, v53, v52
	v_fmac_f32_e32 v53, v54, v51
	v_fma_f32 v18, -v18, v53, v52
	v_div_fmas_f32 v18, v18, v51, v53
	v_div_fixup_f32 v14, v18, v14, v19
	v_add_f32_e32 v18, v20, v50
	v_add_f32_e32 v18, v21, v18
	v_add_f32_e32 v18, v12, v18
	v_add_f32_e32 v18, v13, v18
	v_add_f32_e32 v18, v46, v18
	v_add_f32_e32 v18, v47, v18
	ds_bpermute_b32 v19, v0, v18
	v_mov_b32_e32 v53, v38
	s_waitcnt lgkmcnt(0)
	v_add_f32_e32 v18, v18, v19
	s_nop 1
	s_waitcnt lgkmcnt(0)
	v_add_f32_dpp v18, v18, v18 quad_perm:[2,3,0,1] row_mask:0xf bank_mask:0xf
	s_nop 1
	s_waitcnt lgkmcnt(0)
; DI float siluf(float x) { return x / (1.f + __expf(-x)); }
; DI void pair_finalize(const Params& p, int layer, int kind, int b, int hh) {
;     ...
;       sm += __shfl_xor(sm, 1); sm += __shfl_xor(sm, 2); sm += __shfl_xor(sm, 4);
;       const float mean = kind ? sm * (1.f / 64.f) : 0.f;
;       float ss = 0.f;
; #pragma unroll
;       for (int e = 0; e < 8; ++e) { o[e] -= mean; ss += o[e] * o[e]; }
;       ss += __shfl_xor(ss, 1); ss += __shfl_xor(ss, 2); ss += __shfl_xor(ss, 4);
;       const float rn = rsqrtf(ss * (1.f / 64.f) + 1e-6f);
; #pragma unroll
;       for (int e = 0; e < 8; ++e) o[e] = o[e] * rn * gg[e] * siluf(fz[e]);
;       *(u32x4*)(act + (size_t)row * AP + acol + c8 * 8) = pack8(o);
	v_add_f32_dpp v18, v18, v18 row_half_mirror row_mask:0xf bank_mask:0xf
	v_mul_f32_e32 v18, 0x3c800000, v18
	v_pk_add_f32 v[50:51], v[10:11], v[18:19] op_sel_hi:[1,0] neg_lo:[0,1] neg_hi:[0,1]
	v_pk_add_f32 v[20:21], v[20:21], v[18:19] op_sel_hi:[1,0] neg_lo:[0,1] neg_hi:[0,1]
	v_pk_mul_f32 v[10:11], v[50:51], v[50:51]
	s_nop 0
	v_mov_b32_e32 v52, v10
	v_mov_b32_e32 v38, v11
	v_pk_add_f32 v[10:11], v[52:53], v[38:39]
	v_pk_mul_f32 v[38:39], v[20:21], v[20:21]
	v_pk_add_f32 v[52:53], v[12:13], v[18:19] op_sel_hi:[1,0] neg_lo:[0,1] neg_hi:[0,1]
	v_mov_b32_e32 v54, v38
	v_pk_mul_f32 v[12:13], v[52:53], v[52:53]
	v_pk_add_f32 v[10:11], v[54:55], v[10:11]
	v_mov_b32_e32 v40, v39
	v_pk_add_f32 v[18:19], v[46:47], v[18:19] op_sel_hi:[1,0] neg_lo:[0,1] neg_hi:[0,1]
	v_pk_add_f32 v[10:11], v[40:41], v[10:11]
	v_mov_b32_e32 v38, v12
	v_mov_b32_e32 v39, v42
	v_pk_mul_f32 v[46:47], v[18:19], v[18:19]
	v_pk_add_f32 v[10:11], v[38:39], v[10:11]
	v_mov_b32_e32 v42, v13
	v_pk_add_f32 v[10:11], v[42:43], v[10:11]
	v_mov_b32_e32 v12, v46
	v_mov_b32_e32 v13, v34
	v_pk_add_f32 v[10:11], v[12:13], v[10:11]
	v_mov_b32_e32 v34, v47
	v_pk_add_f32 v[10:11], v[34:35], v[10:11]
	s_nop 1
	v_add_f32_dpp v10, v10, v10 quad_perm:[1,0,3,2] row_mask:0xf bank_mask:0xf
	s_waitcnt lgkmcnt(0)
	v_add_f32_dpp v11, v11, v11 quad_perm:[1,0,3,2] row_mask:0xf bank_mask:0xf
	s_nop 1
	v_add_f32_dpp v10, v10, v10 quad_perm:[2,3,0,1] row_mask:0xf bank_mask:0xf
	s_waitcnt lgkmcnt(0)
	v_add_f32_dpp v11, v11, v11 quad_perm:[2,3,0,1] row_mask:0xf bank_mask:0xf
	s_nop 1
	v_add_f32_dpp v10, v10, v10 row_half_mirror row_mask:0xf bank_mask:0xf
	s_waitcnt lgkmcnt(0)
	v_add_f32_dpp v11, v11, v11 row_half_mirror row_mask:0xf bank_mask:0xf
	s_nop 0
	v_pk_fma_f32 v[34:35], v[10:11], s[10:11], v[80:81] op_sel_hi:[1,0,0]
	s_nop 0
	v_mul_f32_e32 v10, 0x4b800000, v35
	v_cmp_gt_f32_e64 s[0:1], s6, v35
	v_cmp_gt_f32_e32 vcc, s6, v34
	s_nop 0
	v_cndmask_b32_e64 v10, v35, v10, s[0:1]
	v_rsq_f32_e32 v10, v10
	s_nop 0
	v_mul_f32_e32 v11, 0x45800000, v10
	v_cndmask_b32_e64 v10, v10, v11, s[0:1]
	v_pk_mul_f32 v[12:13], v[22:23], v[10:11] op_sel_hi:[1,0]
	v_pk_mul_f32 v[22:23], v[36:37], v[10:11] op_sel_hi:[1,0]
	v_pk_mul_f32 v[12:13], v[6:7], v[12:13]
	v_pk_mul_f32 v[22:23], v[8:9], v[22:23]
	v_pk_mul_f32 v[12:13], v[26:27], v[12:13]
	v_pk_mul_f32 v[26:27], v[32:33], v[10:11] op_sel_hi:[1,0]
	v_pk_mul_f32 v[10:11], v[30:31], v[10:11] op_sel_hi:[1,0]
	v_pk_mul_f32 v[26:27], v[2:3], v[26:27]
	v_pk_mul_f32 v[10:11], v[4:5], v[10:11]
	v_pk_mul_f32 v[22:23], v[28:29], v[22:23]
	v_pk_mul_f32 v[24:25], v[24:25], v[26:27]
	v_pk_mul_f32 v[26:27], v[44:45], v[10:11]
	v_cvt_pk_bf16_f32 v10, v12, v13
	v_cvt_pk_bf16_f32 v11, v22, v23
	v_cvt_pk_bf16_f32 v12, v24, v25
	v_cvt_pk_bf16_f32 v13, v26, v27
	global_store_dwordx4 v[64:65], v[10:13], off
	s_nop 1
	v_mul_f32_e32 v10, 0x4b800000, v34
	v_cndmask_b32_e32 v10, v34, v10, vcc
	v_rsq_f32_e32 v10, v10
	s_nop 0
	v_mul_f32_e32 v11, 0x45800000, v10
	v_cndmask_b32_e32 v10, v10, v11, vcc
	v_pk_mul_f32 v[12:13], v[50:51], v[10:11] op_sel_hi:[1,0]
	s_nop 0
	v_pk_mul_f32 v[12:13], v[6:7], v[12:13]
	s_nop 0
	v_pk_mul_f32 v[12:13], v[14:15], v[12:13]
	v_pk_mul_f32 v[14:15], v[20:21], v[10:11] op_sel_hi:[1,0]
	v_pk_mul_f32 v[20:21], v[52:53], v[10:11] op_sel_hi:[1,0]
	v_mul_f32_e32 v11, 0xbfb8aa3b, v56
	v_pk_mul_f32 v[20:21], v[2:3], v[20:21]
	v_pk_mul_f32 v[14:15], v[8:9], v[14:15]
	v_pk_mul_f32 v[16:17], v[16:17], v[20:21]
	v_exp_f32_e32 v20, v11
	v_pk_mul_f32 v[10:11], v[18:19], v[10:11] op_sel_hi:[1,0]
	v_mul_f32_e32 v18, 0xbfb8aa3b, v57
	v_exp_f32_e32 v21, v18
	v_pk_mul_f32 v[10:11], v[4:5], v[10:11]
	v_pk_mul_f32 v[14:15], v[48:49], v[14:15]
	v_pk_add_f32 v[18:19], v[20:21], 1.0 op_sel_hi:[1,0]
	s_nop 0
	v_div_scale_f32 v20, s[0:1], v19, v19, v57
	v_rcp_f32_e32 v21, v20
	s_nop 0
	v_fma_f32 v22, -v20, v21, 1.0
	v_fmac_f32_e32 v21, v22, v21
	v_div_scale_f32 v22, vcc, v57, v19, v57
	v_mul_f32_e32 v23, v22, v21
	v_fma_f32 v24, -v20, v23, v22
	v_fmac_f32_e32 v23, v24, v21
	v_fma_f32 v20, -v20, v23, v22
	v_div_fmas_f32 v20, v20, v21, v23
	v_div_fixup_f32 v19, v20, v19, v57
	v_div_scale_f32 v20, s[0:1], v18, v18, v56
	v_rcp_f32_e32 v21, v20
	s_nop 0
	v_fma_f32 v22, -v20, v21, 1.0
	v_fmac_f32_e32 v21, v22, v21
	v_div_scale_f32 v22, vcc, v56, v18, v56
	v_mul_f32_e32 v23, v22, v21
	v_fma_f32 v24, -v20, v23, v22
	v_fmac_f32_e32 v23, v24, v21
	v_fma_f32 v20, -v20, v23, v22
	v_div_fmas_f32 v20, v20, v21, v23
	v_div_fixup_f32 v18, v20, v18, v56
	v_pk_mul_f32 v[18:19], v[18:19], v[10:11]
	v_cvt_pk_bf16_f32 v10, v12, v13
	v_cvt_pk_bf16_f32 v11, v14, v15
	v_cvt_pk_bf16_f32 v12, v16, v17
	v_cvt_pk_bf16_f32 v13, v18, v19
	global_store_dwordx4 v[66:67], v[10:13], off
	s_cbranch_scc0 .LBB0_642

; DI int crow(int reg, int h) { return (reg & 3) + 8 * (reg >> 2) + 4 * h; }
; DI void dn_chain(const Params& p, int chain, char* lds) {
;     ...
;   auto rowof = [&](int n, int c) -> int {
;     int cn, base, len;
;     if (n < 4) { cn = n; base = NLAT + b * LC; len = LC; } else { cn = n - 4; base = b * TT; len = TT; }
;     int pos = cn * 64 + c;
;     return base + (dir ? len - 1 - pos : pos);
;   };
;   uint4 pk0, pk1, pq0, pq1, pv0, pv1;
;   float pg = 0.f, pb = 0.f;
;     ...
;   DN_LOAD(0);
;   for (int n = 0; n < 68; ++n) {
;     const uint4 ck0 = pk0, ck1 = pk1, cq0 = pq0, cq1 = pq1, cv0 = pv0, cv1 = pv1;
;     float cgv = pg, cbv = pb;
;     __syncthreads();
;     if (tid < 64) {
;       float v = cgv;
; #pragma unroll
;       for (int o = 1; o < 64; o <<= 1) { float t = __shfl_up(v, o); if (lane >= o) v += t; }
;       gc[tid] = v; bt[tid] = cbv;
;     }
;     *(uint4*)(kA + lc * LS + lp) = ck0;
;     *(uint4*)(kA + (lc + 32) * LS + lp) = ck1;
;     if (n + 1 < 68) DN_LOAD(n + 1);
;     __syncthreads();
;     const float gl = gc[63];
;     f32x16 T;
;     {
;       f32x16 kk = mm64<4>(kA, LS, kA, LS, wm, wn, r, h);
;       const int s = wn * 32 + r;
;       const float gs = gc[s];
; #pragma unroll
;       for (int g = 0; g < 16; ++g) {
;         int c = wm * 32 + crow(g, h);
;         float v = (s < c) ? bt[c] * kk[g] * __expf(gc[c] - gs) : 0.f;
;         kk[g] = v;
;         T[g] = (c == s) ? 1.f : (((c >> 1) == (s >> 1)) ? -v : 0.f);
;     ...
; #pragma unroll
;         for (int g = 0; g < 16; ++g) {
;           int c = wm * 32 + crow(g, h);
;           if ((c >> (k + 1)) == (s >> (k + 1)) && (c >> k) != (s >> k)) T[g] -= X[g];
;         }
.LBB0_652:
	s_or_b64 exec, exec, s[0:1]
	v_ashrrev_i32_e32 v7, 7, v104
	v_and_b32_e32 v13, 31, v104
	s_and_b64 s[0:1], s[42:43], exec
	v_mul_lo_u32 v9, v105, s60
	v_lshlrev_b32_e32 v10, 5, v7
	v_bfe_u32 v3, v104, 5, 1
	s_mov_b32 s0, 0x50cc300
	v_add3_u32 v109, s88, v9, v0
	v_or_b32_e32 v9, v10, v13
	v_bfe_u32 v8, v104, 6, 1
	s_cselect_b32 s4, s0, 0x37c8c100
	s_cselect_b32 s19, s61, 0x100
	s_lshl_b32 s5, s10, 1
	v_mul_lo_u32 v9, v9, s60
	v_lshlrev_b32_e32 v14, 4, v3
	s_add_u32 s0, s64, s5
	s_waitcnt vmcnt(12)
	v_add3_u32 v111, s88, v9, v14
	v_lshl_or_b32 v9, v8, 5, v13
	s_addc_u32 s1, s65, 0
	v_mul_u32_u24_e32 v15, 0x48, v9
	v_lshl_add_u64 v[76:77], s[0:1], 0, v[0:1]
	v_lshl_add_u32 v15, v15, 1, s88
	s_movk_i32 s0, 0xff74
	v_mad_i32_i24 v113, v9, s0, v15
	s_movk_i32 s0, 0x8c
	v_lshlrev_b32_e32 v11, 3, v3
	v_lshl_or_b32 v114, v3, 2, v10
	v_mad_u32_u24 v10, v9, s0, v113
	v_lshlrev_b32_e32 v42, 6, v7
	v_mov_b32_e32 v16, s88
	v_add3_u32 v115, v10, v42, v11
	v_bfe_u32 v43, v104, 2, 2
	v_add_u32_e32 v116, v10, v14
	v_mul_lo_u32 v10, v105, s0
	s_add_u32 s0, s84, s4
	v_mad_u32_u24 v16, v43, s60, v16
	v_lshlrev_b32_e32 v43, 1, v104
	v_lshl_add_u32 v119, v105, 2, s88
	s_addc_u32 s1, s85, 0
	s_lshl_b32 s7, s6, 12
	v_and_b32_e32 v43, 32, v43
	v_add3_u32 v120, v119, v10, v0
	v_lshlrev_b32_e32 v0, 6, v8
	s_add_u32 s0, s0, s5
	v_add3_u32 v44, v16, v42, v43
	v_and_b32_e32 v6, 24, v6
	v_mul_u32_u24_e32 v3, 0x480, v3
	v_add_u32_e32 v10, v16, v0
	s_addc_u32 s1, s1, 0
	v_add3_u32 v117, v44, v6, v3
	v_add3_u32 v118, v15, v42, v11
	v_add3_u32 v6, v10, v43, v6
	v_lshl_add_u64 v[10:11], s[0:1], 0, v[0:1]
	v_readlane_b32 s0, v251, 3
	v_and_b32_e32 v12, 63, v104
	v_readlane_b32 s1, v251, 4
	v_writelane_b32 v252, s10, 42
	v_or_b32_e32 v123, 1, v114
	v_lshl_add_u64 v[4:5], v[4:5], 2, s[0:1]
	v_cmp_eq_u32_e64 s[0:1], 0, v12
	v_or_b32_e32 v124, 2, v114
	v_or_b32_e32 v125, 3, v114
	v_writelane_b32 v252, s0, 43
	v_cmp_lt_i32_e64 s[4:5], v9, v125
	v_or_b32_e32 v126, 8, v114
	v_writelane_b32 v252, s1, 44
	v_cmp_gt_u32_e64 s[0:1], 2, v12
	v_cmp_lt_i32_e64 s[8:9], v9, v126
	v_or_b32_e32 v127, 9, v114
	v_writelane_b32 v252, s0, 45
	v_cmp_lt_i32_e64 s[10:11], v9, v127
	v_or_b32_e32 v128, 10, v114
	v_writelane_b32 v252, s1, 46
	v_cmp_gt_u32_e64 s[0:1], 4, v12
	v_cmp_lt_i32_e64 s[12:13], v9, v128
	v_or_b32_e32 v129, 11, v114
	v_writelane_b32 v252, s0, 47
	v_cmp_lt_i32_e64 s[14:15], v9, v129
	v_or_b32_e32 v130, 16, v114
	v_writelane_b32 v252, s1, 48
	v_cmp_gt_u32_e64 s[0:1], 8, v12
	v_cmp_lt_i32_e64 s[16:17], v9, v130
	v_or_b32_e32 v131, 17, v114
	v_writelane_b32 v252, s0, 49
	v_or_b32_e32 v132, 18, v114
	v_or_b32_e32 v133, 19, v114
	v_writelane_b32 v252, s1, 50
	v_cmp_gt_u32_e64 s[0:1], 16, v12
	v_lshlrev_b32_e32 v0, 1, v13
	v_or_b32_e32 v134, 24, v114
	v_writelane_b32 v252, s0, 51
	v_lshl_add_u64 v[78:79], v[10:11], 0, v[0:1]
	v_lshlrev_b32_e32 v0, 2, v2
	v_writelane_b32 v252, s1, 52
	v_cmp_gt_u32_e64 s[0:1], 32, v12
	v_lshrrev_b32_e32 v17, 1, v9
	v_lshl_add_u64 v[80:81], v[4:5], 0, v[0:1]
	v_writelane_b32 v252, s0, 53
	v_ashrrev_i32_e32 v0, 1, v114
	v_cmp_eq_u32_e64 s[20:21], v0, v17
	v_writelane_b32 v252, s1, 54
	v_cmp_lt_i32_e64 s[0:1], v9, v114
	v_ashrrev_i32_e32 v0, 1, v124
	v_or_b32_e32 v135, 25, v114
	v_writelane_b32 v252, s0, 55
	v_or_b32_e32 v136, 26, v114
	v_or_b32_e32 v137, 27, v114
	v_writelane_b32 v252, s1, 56
	v_cmp_eq_u32_e64 s[0:1], v114, v9
	v_ashrrev_i32_e32 v2, 2, v114
	v_ashrrev_i32_e32 v4, 2, v126
	v_writelane_b32 v252, s0, 57
	v_ashrrev_i32_e32 v5, 2, v127
	v_ashrrev_i32_e32 v10, 2, v128
	v_writelane_b32 v252, s1, 58
	v_cmp_eq_u32_e64 s[0:1], v123, v9
	v_ashrrev_i32_e32 v11, 2, v129
	v_ashrrev_i32_e32 v12, 2, v130
	v_writelane_b32 v252, s0, 59
	v_ashrrev_i32_e32 v13, 2, v131
	v_add_u32_e32 v112, v15, v14
	v_writelane_b32 v252, s1, 60
	v_cmp_lt_i32_e64 s[0:1], v9, v124
	v_ashrrev_i32_e32 v14, 2, v132
	v_ashrrev_i32_e32 v15, 2, v133
	v_writelane_b32 v252, s0, 61
	v_ashrrev_i32_e32 v16, 2, v134
	v_ashrrev_i32_e32 v42, 2, v136
	v_writelane_b32 v252, s1, 62
	v_cmp_eq_u32_e64 s[0:1], v124, v9
	v_ashrrev_i32_e32 v43, 2, v137
	v_lshrrev_b32_e32 v44, 3, v9
	v_writelane_b32 v252, s0, 63
	v_lshlrev_b32_e32 v45, 2, v7
	s_mov_b32 s18, 0
	v_writelane_b32 v253, s1, 0
	v_writelane_b32 v253, s4, 1
	v_cmp_eq_u32_e64 s[0:1], v0, v17
	v_ashrrev_i32_e32 v0, 1, v125
	v_writelane_b32 v253, s5, 2
	v_cmp_eq_u32_e64 s[4:5], v125, v9
	v_add_u32_e32 v110, 0x1200, v109
	v_lshl_add_u32 v121, v104, 2, s88
	v_writelane_b32 v253, s4, 3
	v_lshl_add_u32 v122, v114, 2, s88
	v_cmp_le_i32_e64 s[22:23], v9, v114
	v_writelane_b32 v253, s5, 4
	v_writelane_b32 v253, s8, 5
	v_cmp_eq_u32_e64 s[4:5], v0, v17
	v_ashrrev_i32_e32 v0, 1, v126
	v_writelane_b32 v253, s9, 6
	v_cmp_eq_u32_e64 s[8:9], v126, v9
	v_cmp_le_i32_e64 s[46:47], v9, v123
	v_cmp_le_i32_e64 s[58:59], v9, v125
	v_writelane_b32 v253, s8, 7
	v_cmp_le_i32_e64 s[60:61], v9, v126
	v_cmp_le_i32_e64 s[82:83], v9, v128
	v_writelane_b32 v253, s9, 8
	v_writelane_b32 v253, s10, 9
	v_cmp_eq_u32_e64 s[8:9], v0, v17
	v_ashrrev_i32_e32 v0, 1, v127
	v_writelane_b32 v253, s11, 10
	v_cmp_eq_u32_e64 s[10:11], v127, v9
	v_cmp_le_i32_e64 s[84:85], v9, v129
	v_cmp_le_i32_e64 s[88:89], v9, v130
	v_writelane_b32 v253, s10, 11
	v_cmp_le_i32_e64 s[64:65], v9, v131
	v_cmp_le_i32_e64 s[66:67], v9, v133
	v_writelane_b32 v253, s11, 12
	v_writelane_b32 v253, s12, 13
	v_cmp_eq_u32_e64 s[10:11], v0, v17
	v_ashrrev_i32_e32 v0, 1, v128
	v_writelane_b32 v253, s13, 14
	v_cmp_eq_u32_e64 s[12:13], v128, v9
	v_cmp_le_i32_e64 s[70:71], v9, v134
	v_cmp_le_i32_e64 s[72:73], v9, v135
	v_writelane_b32 v253, s12, 15
	v_cmp_le_i32_e64 s[76:77], v9, v136
	v_cmp_le_i32_e64 s[78:79], v9, v137
; DI int crow(int reg, int h) { return (reg & 3) + 8 * (reg >> 2) + 4 * h; }
; DI void dn_chain(const Params& p, int chain, char* lds) {
;     ...
;       f32x16 kk = mm64<4>(kA, LS, kA, LS, wm, wn, r, h);
;       const int s = wn * 32 + r;
;       const float gs = gc[s];
; #pragma unroll
;       for (int g = 0; g < 16; ++g) {
;         int c = wm * 32 + crow(g, h);
;         float v = (s < c) ? bt[c] * kk[g] * __expf(gc[c] - gs) : 0.f;
;         kk[g] = v;
;         T[g] = (c == s) ? 1.f : (((c >> 1) == (s >> 1)) ? -v : 0.f);
;     ...
;       {
;         const int s = wn * 32 + r;
; #pragma unroll
;         for (int g = 0; g < 16; ++g) {
;           int c = wm * 32 + crow(g, h);
;           if ((c >> (k + 1)) == (s >> (k + 1)) && (c >> k) != (s >> k)) T[g] -= X[g];
;         }
	v_writelane_b32 v253, s13, 16
	v_writelane_b32 v253, s14, 17
	v_cmp_eq_u32_e64 s[12:13], v0, v17
	v_ashrrev_i32_e32 v0, 1, v129
	v_writelane_b32 v253, s15, 18
	v_cmp_eq_u32_e64 s[14:15], v129, v9
	v_add_u32_e32 v138, v6, v3
	v_mov_b32_e32 v75, v74
	v_writelane_b32 v253, s14, 19
	v_mov_b32_e32 v82, v74
	v_mov_b32_e32 v83, v74
	v_writelane_b32 v253, s15, 20
	v_writelane_b32 v253, s16, 21
	v_cmp_eq_u32_e64 s[14:15], v0, v17
	v_ashrrev_i32_e32 v0, 1, v130
	v_writelane_b32 v253, s17, 22
	v_cmp_eq_u32_e64 s[16:17], v130, v9
	v_cmp_eq_u32_e64 s[24:25], v0, v17
	v_ashrrev_i32_e32 v0, 1, v131
	v_writelane_b32 v253, s16, 23
	v_cmp_eq_u32_e64 s[26:27], v0, v17
	v_ashrrev_i32_e32 v0, 1, v132
	v_writelane_b32 v253, s17, 24
	v_cmp_lt_i32_e64 s[16:17], v9, v131
	v_cmp_eq_u32_e64 s[28:29], v0, v17
	v_ashrrev_i32_e32 v0, 1, v133
	v_writelane_b32 v253, s16, 25
	v_cmp_eq_u32_e64 s[30:31], v0, v17
	v_ashrrev_i32_e32 v0, 1, v134
	v_writelane_b32 v253, s17, 26
	v_cmp_eq_u32_e64 s[16:17], v131, v9
	v_cmp_eq_u32_e64 s[34:35], v0, v17
	v_ashrrev_i32_e32 v0, 1, v135
	v_writelane_b32 v253, s16, 27
	v_cmp_eq_u32_e64 s[36:37], v0, v17
	v_ashrrev_i32_e32 v0, 1, v136
	v_writelane_b32 v253, s17, 28
	v_cmp_lt_i32_e64 s[16:17], v9, v132
	v_cmp_eq_u32_e64 s[38:39], v0, v17
	v_ashrrev_i32_e32 v0, 1, v137
	v_writelane_b32 v253, s16, 29
	v_cmp_eq_u32_e64 s[44:45], v0, v17
	v_lshrrev_b32_e32 v0, 2, v9
	v_writelane_b32 v253, s17, 30
	v_cmp_eq_u32_e64 s[16:17], v132, v9
	v_cmp_ne_u32_e32 vcc, v2, v0
	v_ashrrev_i32_e32 v17, 2, v135
	v_writelane_b32 v253, s16, 31
	v_mov_b32_e32 v84, v74
	v_mov_b32_e32 v85, v74
	v_writelane_b32 v253, s17, 32
	v_cmp_lt_i32_e64 s[16:17], v9, v133
	v_mov_b32_e32 v86, v74
	v_mov_b32_e32 v87, v74
	v_writelane_b32 v253, s16, 33
	v_mov_b32_e32 v88, v74
	v_mov_b32_e32 v89, v74
	v_writelane_b32 v253, s17, 34
	v_cmp_eq_u32_e64 s[16:17], v133, v9
	v_mov_b32_e32 v90, v74
	v_mov_b32_e32 v91, v74
	v_writelane_b32 v253, s16, 35
	v_mov_b32_e32 v92, v74
	v_mov_b32_e32 v93, v74
	v_writelane_b32 v253, s17, 36
	v_cmp_lt_i32_e64 s[16:17], v9, v134
	v_mov_b32_e32 v94, v74
	v_mov_b32_e32 v95, v74
	v_writelane_b32 v253, s16, 37
	s_nop 1
	v_writelane_b32 v253, s17, 38
	v_cmp_eq_u32_e64 s[16:17], v134, v9
	s_nop 1
	v_writelane_b32 v253, s16, 39
	s_nop 1
	v_writelane_b32 v253, s17, 40
	v_cmp_lt_i32_e64 s[16:17], v9, v135
	s_nop 1
	v_writelane_b32 v253, s16, 41
	s_nop 1
	v_writelane_b32 v253, s17, 42
	v_cmp_eq_u32_e64 s[16:17], v135, v9
	s_nop 1
	v_writelane_b32 v253, s16, 43
	s_nop 1
	v_writelane_b32 v253, s17, 44
	v_cmp_lt_i32_e64 s[16:17], v9, v136
	s_nop 1
	v_writelane_b32 v253, s16, 45
	s_nop 1
	v_writelane_b32 v253, s17, 46
	v_cmp_eq_u32_e64 s[16:17], v136, v9
	s_nop 1
	v_writelane_b32 v253, s16, 47
	s_nop 1
	v_writelane_b32 v253, s17, 48
	v_cmp_lt_i32_e64 s[16:17], v9, v137
	s_nop 1
	v_writelane_b32 v253, s16, 49
	s_nop 1
	v_writelane_b32 v253, s17, 50
	v_cmp_eq_u32_e64 s[16:17], v137, v9
	s_nop 1
	v_writelane_b32 v253, s16, 51
	s_nop 1
	v_writelane_b32 v253, s17, 52
	v_writelane_b32 v253, s0, 53
	s_or_b64 s[16:17], vcc, s[20:21]
	s_nop 0
	v_writelane_b32 v253, s1, 54
	s_or_b64 s[0:1], vcc, s[0:1]
	v_writelane_b32 v253, s0, 55
	s_nop 1
	v_writelane_b32 v253, s1, 56
	v_writelane_b32 v253, s4, 57
	s_or_b64 s[0:1], vcc, s[4:5]
	v_cmp_ne_u32_e32 vcc, v4, v0
	v_writelane_b32 v253, s5, 58
	v_writelane_b32 v253, s0, 59
	s_movk_i32 s4, 0xff
	s_nop 0
	v_writelane_b32 v253, s1, 60
	v_writelane_b32 v253, s8, 61
	s_or_b64 s[0:1], vcc, s[8:9]
	v_cmp_ne_u32_e32 vcc, v5, v0
	v_writelane_b32 v253, s9, 62
	v_writelane_b32 v253, s0, 63
	v_cmp_eq_u32_e64 s[8:9], v7, v8
	s_nop 0
	v_writelane_b32 v254, s1, 0
	v_writelane_b32 v254, s10, 1
	s_or_b64 s[0:1], vcc, s[10:11]
	v_cmp_ne_u32_e32 vcc, v10, v0
	v_writelane_b32 v254, s11, 2
	v_writelane_b32 v254, s0, 3
	s_nop 1
	v_writelane_b32 v254, s1, 4
	v_writelane_b32 v254, s12, 5
	s_or_b64 s[0:1], vcc, s[12:13]
	v_cmp_ne_u32_e32 vcc, v11, v0
	v_writelane_b32 v254, s13, 6
	v_writelane_b32 v254, s0, 7
	s_nop 1
	v_writelane_b32 v254, s1, 8
	v_writelane_b32 v254, s14, 9
	s_or_b64 s[0:1], vcc, s[14:15]
	v_cmp_ne_u32_e32 vcc, v12, v0
	v_writelane_b32 v254, s15, 10
	v_writelane_b32 v254, s0, 11
	v_cmp_le_i32_e64 s[14:15], v9, v127
	s_nop 0
	v_writelane_b32 v254, s1, 12
	v_writelane_b32 v254, s24, 13
	s_or_b64 s[0:1], vcc, s[24:25]
	v_cmp_ne_u32_e32 vcc, v13, v0
	v_writelane_b32 v254, s25, 14
	v_writelane_b32 v254, s0, 15
	s_mov_b32 s25, 0
	s_nop 0
	v_writelane_b32 v254, s1, 16
	v_writelane_b32 v254, s26, 17
	s_or_b64 s[0:1], vcc, s[26:27]
	v_cmp_ne_u32_e32 vcc, v14, v0
	v_writelane_b32 v254, s27, 18
	v_writelane_b32 v254, s0, 19
	s_nop 1
	v_writelane_b32 v254, s1, 20
	v_writelane_b32 v254, s28, 21
	s_or_b64 s[0:1], vcc, s[28:29]
	v_cmp_ne_u32_e32 vcc, v15, v0
	v_writelane_b32 v254, s29, 22
	v_writelane_b32 v254, s0, 23
	s_nop 1
	v_writelane_b32 v254, s1, 24
	v_writelane_b32 v254, s30, 25
	s_or_b64 s[0:1], vcc, s[30:31]
	v_cmp_ne_u32_e32 vcc, v16, v0
	v_writelane_b32 v254, s31, 26
	v_writelane_b32 v254, s0, 27
	s_nop 1
	v_writelane_b32 v254, s1, 28
	v_writelane_b32 v254, s34, 29
	s_or_b64 s[0:1], vcc, s[34:35]
	v_cmp_ne_u32_e32 vcc, v17, v0
	v_writelane_b32 v254, s35, 30
	v_writelane_b32 v254, s0, 31
	s_nop 1
	v_writelane_b32 v254, s1, 32
	v_writelane_b32 v254, s36, 33
	s_or_b64 s[0:1], vcc, s[36:37]
	v_cmp_ne_u32_e32 vcc, v42, v0
	v_writelane_b32 v254, s37, 34
	v_writelane_b32 v254, s0, 35
	s_nop 1
	v_writelane_b32 v254, s1, 36
	v_writelane_b32 v254, s38, 37
	s_or_b64 s[0:1], vcc, s[38:39]
	v_cmp_ne_u32_e32 vcc, v43, v0
	v_writelane_b32 v254, s39, 38
	v_writelane_b32 v254, s0, 39
	v_cmp_le_i32_e64 s[38:39], v9, v132
	s_nop 0
	v_writelane_b32 v254, s1, 40
; DI int crow(int reg, int h) { return (reg & 3) + 8 * (reg >> 2) + 4 * h; }
; DI void dn_chain(const Params& p, int chain, char* lds) {
;     ...
;     for (int k = 1; k < 6; ++k) {
;       f32x16 M = mm64t<4>(R1, LS, R2, LS, wm, wn, r, h, lane);
;       st_transp(R4, LS, M, wm, wn, r, h);
;       __syncthreads();
;       f32x16 X = mm64t<4>(R2, LS, R4, LS, wm, wn, r, h, lane);
;       {
;         const int s = wn * 32 + r;
; #pragma unroll
;         for (int g = 0; g < 16; ++g) {
;           int c = wm * 32 + crow(g, h);
;           if ((c >> (k + 1)) == (s >> (k + 1)) && (c >> k) != (s >> k)) T[g] -= X[g];
;         }
;       }
	v_writelane_b32 v254, s44, 41
	s_or_b64 s[0:1], vcc, s[44:45]
	v_cmp_ne_u32_e32 vcc, v45, v44
	v_writelane_b32 v254, s45, 42
	v_writelane_b32 v254, s0, 43
	s_nop 1
	v_writelane_b32 v254, s1, 44
	v_cmp_eq_u32_e64 s[0:1], v2, v0
	v_ashrrev_i32_e32 v2, 3, v126
	s_or_b64 s[30:31], vcc, s[0:1]
	v_cmp_ne_u32_e32 vcc, v2, v44
	v_cmp_eq_u32_e64 s[0:1], v4, v0
	s_or_b64 s[0:1], vcc, s[0:1]
	v_ashrrev_i32_e32 v4, 3, v127
	v_writelane_b32 v254, s0, 45
	v_cmp_ne_u32_e32 vcc, v4, v44
	s_nop 0
	v_writelane_b32 v254, s1, 46
	v_cmp_eq_u32_e64 s[0:1], v5, v0
	s_or_b64 s[0:1], vcc, s[0:1]
	v_ashrrev_i32_e32 v5, 3, v128
	v_writelane_b32 v254, s0, 47
	v_cmp_ne_u32_e32 vcc, v5, v44
	s_nop 0
	v_writelane_b32 v254, s1, 48
	v_cmp_eq_u32_e64 s[0:1], v10, v0
	s_or_b64 s[0:1], vcc, s[0:1]
	v_ashrrev_i32_e32 v10, 3, v129
	v_writelane_b32 v254, s0, 49
	v_cmp_ne_u32_e32 vcc, v10, v44
	s_nop 0
	v_writelane_b32 v254, s1, 50
	v_cmp_eq_u32_e64 s[0:1], v11, v0
	s_or_b64 s[0:1], vcc, s[0:1]
	v_ashrrev_i32_e32 v11, 3, v130
	v_writelane_b32 v254, s0, 51
	v_cmp_ne_u32_e32 vcc, v11, v44
	s_nop 0
	v_writelane_b32 v254, s1, 52
	v_cmp_eq_u32_e64 s[0:1], v12, v0
	s_or_b64 s[0:1], vcc, s[0:1]
	v_ashrrev_i32_e32 v12, 3, v131
	v_writelane_b32 v254, s0, 53
	v_cmp_ne_u32_e32 vcc, v12, v44
	s_nop 0
	v_writelane_b32 v254, s1, 54
	v_cmp_eq_u32_e64 s[0:1], v13, v0
	s_or_b64 s[0:1], vcc, s[0:1]
	v_ashrrev_i32_e32 v13, 3, v132
	v_writelane_b32 v254, s0, 55
	v_cmp_ne_u32_e32 vcc, v13, v44
	s_nop 0
	v_writelane_b32 v254, s1, 56
	v_cmp_eq_u32_e64 s[0:1], v14, v0
	s_or_b64 s[0:1], vcc, s[0:1]
	v_ashrrev_i32_e32 v14, 3, v133
	v_writelane_b32 v254, s0, 57
	v_cmp_ne_u32_e32 vcc, v14, v44
	s_nop 0
	v_writelane_b32 v254, s1, 58
	v_cmp_eq_u32_e64 s[0:1], v15, v0
	s_or_b64 s[0:1], vcc, s[0:1]
	v_ashrrev_i32_e32 v15, 3, v134
	v_writelane_b32 v254, s0, 59
	v_cmp_ne_u32_e32 vcc, v15, v44
	s_nop 0
	v_writelane_b32 v254, s1, 60
	v_cmp_eq_u32_e64 s[0:1], v16, v0
	s_or_b64 s[0:1], vcc, s[0:1]
	v_ashrrev_i32_e32 v16, 3, v135
	v_writelane_b32 v254, s0, 61
	v_cmp_ne_u32_e32 vcc, v16, v44
	s_nop 0
	v_writelane_b32 v254, s1, 62
	v_cmp_eq_u32_e64 s[0:1], v17, v0
	s_or_b64 s[0:1], vcc, s[0:1]
	v_ashrrev_i32_e32 v17, 3, v136
	v_writelane_b32 v254, s0, 63
	v_cmp_ne_u32_e32 vcc, v17, v44
	s_nop 0
	v_writelane_b32 v255, s1, 0
	v_cmp_eq_u32_e64 s[0:1], v42, v0
	s_or_b64 s[0:1], vcc, s[0:1]
	v_ashrrev_i32_e32 v42, 3, v137
	v_writelane_b32 v255, s0, 1
	v_cmp_ne_u32_e32 vcc, v42, v44
	s_nop 0
	v_writelane_b32 v255, s1, 2
	v_cmp_eq_u32_e64 s[0:1], v43, v0
	s_or_b64 s[0:1], vcc, s[0:1]
	v_lshrrev_b32_e32 v0, 4, v9
	v_writelane_b32 v255, s0, 3
	v_lshlrev_b32_e32 v43, 1, v7
	v_cmp_ne_u32_e32 vcc, v43, v0
	v_writelane_b32 v255, s1, 4
	v_cmp_eq_u32_e64 s[0:1], v45, v44
	s_or_b64 s[90:91], vcc, s[0:1]
	v_cmp_eq_u32_e64 s[0:1], v2, v44
	s_or_b64 s[0:1], vcc, s[0:1]
	v_ashrrev_i32_e32 v2, 4, v130
	v_writelane_b32 v255, s0, 5
	s_nop 1
	v_writelane_b32 v255, s1, 6
	v_cmp_eq_u32_e64 s[0:1], v4, v44
	s_or_b64 s[0:1], vcc, s[0:1]
	v_ashrrev_i32_e32 v4, 4, v131
	v_writelane_b32 v255, s0, 7
	s_nop 1
	v_writelane_b32 v255, s1, 8
	v_cmp_eq_u32_e64 s[0:1], v5, v44
	s_or_b64 s[0:1], vcc, s[0:1]
	v_ashrrev_i32_e32 v5, 4, v132
	v_writelane_b32 v255, s0, 9
	s_nop 1
	v_writelane_b32 v255, s1, 10
	v_cmp_eq_u32_e64 s[0:1], v10, v44
	s_or_b64 s[0:1], vcc, s[0:1]
	v_cmp_ne_u32_e32 vcc, v2, v0
	v_writelane_b32 v255, s0, 11
	v_ashrrev_i32_e32 v10, 4, v133
	s_nop 0
	v_writelane_b32 v255, s1, 12
	v_cmp_eq_u32_e64 s[0:1], v11, v44
	s_or_b64 s[0:1], vcc, s[0:1]
	v_cmp_ne_u32_e32 vcc, v4, v0
	v_writelane_b32 v255, s0, 13
	v_ashrrev_i32_e32 v11, 4, v134
	s_nop 0
	v_writelane_b32 v255, s1, 14
	v_cmp_eq_u32_e64 s[0:1], v12, v44
	s_or_b64 s[0:1], vcc, s[0:1]
	v_cmp_ne_u32_e32 vcc, v5, v0
	v_writelane_b32 v255, s0, 15
	v_ashrrev_i32_e32 v12, 4, v135
	s_nop 0
	v_writelane_b32 v255, s1, 16
	v_cmp_eq_u32_e64 s[0:1], v13, v44
	s_or_b64 s[0:1], vcc, s[0:1]
	v_cmp_ne_u32_e32 vcc, v10, v0
	v_writelane_b32 v255, s0, 17
	v_ashrrev_i32_e32 v13, 4, v136
	s_nop 0
	v_writelane_b32 v255, s1, 18
	v_cmp_eq_u32_e64 s[0:1], v14, v44
	s_or_b64 s[0:1], vcc, s[0:1]
	v_cmp_ne_u32_e32 vcc, v11, v0
	v_writelane_b32 v255, s0, 19
	v_ashrrev_i32_e32 v14, 4, v137
	s_nop 0
	v_writelane_b32 v255, s1, 20
	v_cmp_eq_u32_e64 s[0:1], v15, v44
	s_or_b64 s[0:1], vcc, s[0:1]
	v_cmp_ne_u32_e32 vcc, v12, v0
	v_writelane_b32 v255, s0, 21
	s_nop 1
	v_writelane_b32 v255, s1, 22
	v_cmp_eq_u32_e64 s[0:1], v16, v44
	s_or_b64 s[0:1], vcc, s[0:1]
	v_cmp_ne_u32_e32 vcc, v13, v0
	v_writelane_b32 v255, s0, 23
	s_nop 1
	v_writelane_b32 v255, s1, 24
	v_cmp_eq_u32_e64 s[0:1], v17, v44
	s_or_b64 s[0:1], vcc, s[0:1]
	v_cmp_ne_u32_e32 vcc, v14, v0
	v_writelane_b32 v255, s0, 25
	s_nop 1
	v_writelane_b32 v255, s1, 26
	v_cmp_eq_u32_e64 s[0:1], v42, v44
	s_or_b64 s[0:1], vcc, s[0:1]
	v_cmp_ne_u32_e32 vcc, v7, v8
	v_writelane_b32 v255, s0, 27
	s_nop 1
	v_writelane_b32 v255, s1, 28
	v_cmp_eq_u32_e64 s[0:1], v43, v0
	s_or_b64 s[80:81], vcc, s[0:1]
	v_cmp_eq_u32_e64 s[0:1], v2, v0
	s_or_b64 s[0:1], vcc, s[0:1]
	s_nop 0
	v_writelane_b32 v255, s0, 29
	s_nop 1
	v_writelane_b32 v255, s1, 30
	v_cmp_eq_u32_e64 s[0:1], v4, v0
	s_or_b64 s[0:1], vcc, s[0:1]
	s_nop 0
	v_writelane_b32 v255, s0, 31
	s_nop 1
	v_writelane_b32 v255, s1, 32
	v_cmp_eq_u32_e64 s[0:1], v5, v0
	s_or_b64 s[10:11], vcc, s[0:1]
	v_cmp_eq_u32_e64 s[0:1], v10, v0
	s_or_b64 s[34:35], vcc, s[0:1]
	v_cmp_eq_u32_e64 s[0:1], v11, v0
	s_or_b64 s[36:37], vcc, s[0:1]
	v_cmp_eq_u32_e64 s[0:1], v12, v0
	s_or_b64 s[12:13], vcc, s[0:1]
	v_cmp_eq_u32_e64 s[0:1], v13, v0
	s_or_b64 s[28:29], vcc, s[0:1]
	v_cmp_eq_u32_e64 s[0:1], v14, v0
	s_or_b64 s[0:1], vcc, s[0:1]
	v_cmp_lt_u32_e32 vcc, s4, v104
	s_or_b64 s[44:45], vcc, s[8:9]
	v_cmp_le_i32_e64 s[8:9], v9, v124
	s_waitcnt vmcnt(0)
	s_branch .LBB0_654

; DI void dn_chain(const Params& p, int chain, char* lds) {
;     ...
;   for (int n = 0; n < 68; ++n) {
;     const uint4 ck0 = pk0, ck1 = pk1, cq0 = pq0, cq1 = pq1, cv0 = pv0, cv1 = pv1;
;     float cgv = pg, cbv = pb;
;     __syncthreads();
;     if (tid < 64) {
;       float v = cgv;
; #pragma unroll
;       for (int o = 1; o < 64; o <<= 1) { float t = __shfl_up(v, o); if (lane >= o) v += t; }
;       gc[tid] = v; bt[tid] = cbv;
;     }
;     *(uint4*)(kA + lc * LS + lp) = ck0;
;     *(uint4*)(kA + (lc + 32) * LS + lp) = ck1;
;     if (n + 1 < 68) DN_LOAD(n + 1);
.LBB0_654:
	s_waitcnt lgkmcnt(0)
	s_barrier
	s_and_saveexec_b64 s[4:5], s[2:3]
	s_cbranch_execz .LBB0_656
	v_and_b32_e32 v0, 64, v209
	v_add_u32_e32 v2, -1, v209
	v_cmp_lt_i32_e32 vcc, v2, v0
	v_add_u32_e32 v3, -2, v209
	v_readlane_b32 s26, v252, 43
	v_cndmask_b32_e32 v2, v2, v209, vcc
	v_lshlrev_b32_e32 v2, 2, v2
	s_waitcnt vmcnt(16)
	ds_bpermute_b32 v2, v2, v107
	v_cmp_lt_i32_e32 vcc, v3, v0
	v_readlane_b32 s27, v252, 44
	s_waitcnt lgkmcnt(0)
	v_add_f32_e32 v2, v107, v2
	v_cndmask_b32_e32 v3, v3, v209, vcc
	v_cndmask_b32_e64 v2, v2, v107, s[26:27]
	v_lshlrev_b32_e32 v3, 2, v3
	ds_bpermute_b32 v3, v3, v2
	v_readlane_b32 s26, v252, 45
	v_readlane_b32 s27, v252, 46
	s_waitcnt lgkmcnt(0)
	v_add_f32_e32 v3, v2, v3
	v_cndmask_b32_e64 v2, v3, v2, s[26:27]
	v_add_u32_e32 v3, -4, v209
	v_cmp_lt_i32_e32 vcc, v3, v0
	v_readlane_b32 s26, v252, 47
	v_readlane_b32 s27, v252, 48
	v_cndmask_b32_e32 v3, v3, v209, vcc
	v_lshlrev_b32_e32 v3, 2, v3
	ds_bpermute_b32 v3, v3, v2
	s_waitcnt lgkmcnt(0)
	v_add_f32_e32 v3, v2, v3
	v_cndmask_b32_e64 v2, v3, v2, s[26:27]
	v_add_u32_e32 v3, -8, v209
	v_cmp_lt_i32_e32 vcc, v3, v0
	v_readlane_b32 s26, v252, 49
	v_readlane_b32 s27, v252, 50
	v_cndmask_b32_e32 v3, v3, v209, vcc
	v_lshlrev_b32_e32 v3, 2, v3
	ds_bpermute_b32 v3, v3, v2
	s_waitcnt lgkmcnt(0)
	v_add_f32_e32 v3, v2, v3
	v_cndmask_b32_e64 v2, v3, v2, s[26:27]
	v_add_u32_e32 v3, -16, v209
	v_cmp_lt_i32_e32 vcc, v3, v0
	v_readlane_b32 s26, v252, 51
	v_readlane_b32 s27, v252, 52
	v_cndmask_b32_e32 v3, v3, v209, vcc
	v_lshlrev_b32_e32 v3, 2, v3
	ds_bpermute_b32 v3, v3, v2
	s_waitcnt lgkmcnt(0)
	v_add_f32_e32 v3, v2, v3
	v_cndmask_b32_e64 v2, v3, v2, s[26:27]
	v_subrev_u32_e32 v3, 32, v209
	v_cmp_lt_i32_e32 vcc, v3, v0
	v_readlane_b32 s26, v252, 53
	v_readlane_b32 s27, v252, 54
	v_cndmask_b32_e32 v0, v3, v209, vcc
	v_lshlrev_b32_e32 v0, 2, v0
	ds_bpermute_b32 v0, v0, v2
	s_waitcnt lgkmcnt(0)
	v_add_f32_e32 v0, v2, v0
	v_cndmask_b32_e64 v0, v0, v2, s[26:27]
	s_waitcnt vmcnt(16)
	ds_write2st64_b32 v121, v0, v108 offset0:252 offset1:253
.LBB0_656:
	s_or_b64 exec, exec, s[4:5]
	s_add_i32 s24, s25, 1
	s_cmpk_eq_i32 s25, 0x43
	s_waitcnt vmcnt(16)
	ds_write_b128 v109, v[30:33]
	s_waitcnt vmcnt(16)
	ds_write_b128 v110, v[26:29]
	s_cbranch_scc1 .LBB0_660
	v_mov_b32_e32 v0, s24
	v_sub_co_u32_e64 v2, vcc, s25, 3
	s_and_b64 s[4:5], vcc, exec
	s_nop 0
	v_cndmask_b32_e32 v0, v2, v0, vcc
	s_movk_i32 s4, 0xff
	v_lshlrev_b32_e32 v0, 6, v0
	s_cselect_b32 vcc_hi, s4, 0xfff
	v_add_u32_e32 v2, v0, v105
	v_sub_u32_e32 v3, vcc_hi, v2
	v_add_u32_e32 v4, v0, v106
	s_cselect_b32 vcc_lo, s41, s7
	v_cndmask_b32_e64 v2, v3, v2, s[42:43]
	v_sub_u32_e32 v5, vcc_hi, v4
	v_add_u32_e32 v2, vcc_lo, v2
	s_movk_i32 s26, 0x600
	v_cndmask_b32_e64 v4, v5, v4, s[42:43]
	v_mad_i64_i32 v[2:3], s[4:5], v2, s26, v[76:77]
	v_add_u32_e32 v4, vcc_lo, v4
	v_mad_i64_i32 v[4:5], s[4:5], v4, s26, v[76:77]
	global_load_dwordx4 v[58:61], v[2:3], off
	global_load_dwordx4 v[66:69], v[2:3], off offset:512
	global_load_dwordx4 v[50:53], v[2:3], off offset:1024
	global_load_dwordx4 v[62:65], v[4:5], off
	global_load_dwordx4 v[70:73], v[4:5], off offset:512
	global_load_dwordx4 v[54:57], v[4:5], off offset:1024
	s_and_saveexec_b64 s[4:5], s[2:3]
	s_cbranch_execz .LBB0_659
	v_add_u32_e32 v0, v0, v104
	v_sub_u32_e32 v2, vcc_hi, v0
	v_cndmask_b32_e64 v0, v2, v0, s[42:43]
	v_add_u32_e32 v2, vcc_lo, v0
	v_ashrrev_i32_e32 v3, 31, v2
	v_lshlrev_b64 v[2:3], 6, v[2:3]
	v_lshl_add_u64 v[2:3], v[80:81], 0, v[2:3]
	global_load_dword v107, v[2:3], off
	global_load_dword v108, v[2:3], off offset:32

; DI float siluf(float x) { return x / (1.f + __expf(-x)); }
; DI void pair_finalize(const Params& p, int layer, int kind, int b, int hh) {
;     ...
;   for (int j0 = 0; j0 < 68; j0 += 4) {
;     u32x4 a[4], bw[4], z[4];
; #pragma unroll
;     for (int u = 0; u < 4; ++u) {
;       const int rr = (ltid + 512 * (j0 + u)) >> 3;
;       const int row = rr < TT ? b * TT + rr : NLAT + b * LC + (rr - TT);
;       a[u] = ldg16(act + (size_t)row * AP + acol + c8 * 8);
;       bw[u] = ldg16(BW + (size_t)row * 256 + c8 * 8);
;       z[u] = ldg16(Z + (size_t)row * ZW + zcol + c8 * 8);
;     }
; #pragma unroll
;     for (int u = 0; u < 4; ++u) {
;       const int rr = (ltid + 512 * (j0 + u)) >> 3;
;       const int row = rr < TT ? b * TT + rr : NLAT + b * LC + (rr - TT);
;       float fa[8], fb[8], fz[8], o[8];
;       unpack8(a[u], fa); unpack8(bw[u], fb); unpack8(z[u], fz);
;       float sm = 0.f;
; #pragma unroll
;       for (int e = 0; e < 8; ++e) { o[e] = fa[e] + fb[e]; sm += o[e]; }
;       sm += __shfl_xor(sm, 1); sm += __shfl_xor(sm, 2); sm += __shfl_xor(sm, 4);
;       const float mean = kind ? sm * (1.f / 64.f) : 0.f;
;       float ss = 0.f;
; #pragma unroll
;       for (int e = 0; e < 8; ++e) { o[e] -= mean; ss += o[e] * o[e]; }
;       ss += __shfl_xor(ss, 1); ss += __shfl_xor(ss, 2); ss += __shfl_xor(ss, 4);
;       const float rn = rsqrtf(ss * (1.f / 64.f) + 1e-6f);
; #pragma unroll
;       for (int e = 0; e < 8; ++e) o[e] = o[e] * rn * gg[e] * siluf(fz[e]);
.LBB0_726:
	v_ashrrev_i32_e32 v10, 3, v84
	v_cmp_gt_i32_e32 vcc, s5, v10
	v_mov_b32_e32 v14, s2
	v_mov_b32_e32 v15, s7
	v_cndmask_b32_e32 v11, v14, v15, vcc
	v_add_u32_e32 v10, v11, v10
	v_ashrrev_i32_e32 v11, 31, v10
	v_lshlrev_b64 v[12:13], 9, v[10:11]
	v_mad_i64_i32 v[68:69], s[0:1], v10, s4, v[58:59]
	v_lshl_add_u64 v[12:13], v[60:61], 0, v[12:13]
	v_mad_i64_i32 v[10:11], s[0:1], v10, s87, v[62:63]
	global_load_dwordx4 v[46:49], v[68:69], off
	global_load_dwordx4 v[50:53], v[12:13], off
	global_load_dwordx4 v[54:57], v[10:11], off
	v_add_u32_e32 v10, 0x200, v84
	v_ashrrev_i32_e32 v10, 3, v10
	v_cmp_gt_i32_e32 vcc, s5, v10
	s_add_i32 s3, s3, 4
	s_cmp_gt_u32 s3, 63
	v_cndmask_b32_e32 v11, v14, v15, vcc
	v_add_u32_e32 v10, v11, v10
	v_ashrrev_i32_e32 v11, 31, v10
	v_mad_i64_i32 v[70:71], s[0:1], v10, s4, v[58:59]
	v_lshlrev_b64 v[12:13], 9, v[10:11]
	v_mad_i64_i32 v[10:11], s[0:1], v10, s87, v[62:63]
	global_load_dwordx4 v[42:45], v[10:11], off
	v_add_u32_e32 v10, 0x400, v84
	v_ashrrev_i32_e32 v10, 3, v10
	v_cmp_gt_i32_e32 vcc, s5, v10
	v_lshl_add_u64 v[12:13], v[60:61], 0, v[12:13]
	global_load_dwordx4 v[38:41], v[12:13], off
	v_cndmask_b32_e32 v11, v14, v15, vcc
	v_add_u32_e32 v10, v11, v10
	v_ashrrev_i32_e32 v11, 31, v10
	v_mad_i64_i32 v[64:65], s[0:1], v10, s4, v[58:59]
	v_lshlrev_b64 v[12:13], 9, v[10:11]
	v_mad_i64_i32 v[10:11], s[0:1], v10, s87, v[62:63]
	global_load_dwordx4 v[30:33], v[10:11], off
	v_add_u32_e32 v10, 0x600, v84
	v_ashrrev_i32_e32 v10, 3, v10
	v_cmp_gt_i32_e32 vcc, s5, v10
	global_load_dwordx4 v[34:37], v[70:71], off
	v_lshl_add_u64 v[12:13], v[60:61], 0, v[12:13]
	v_cndmask_b32_e32 v11, v14, v15, vcc
	global_load_dwordx4 v[22:25], v[64:65], off
	global_load_dwordx4 v[26:29], v[12:13], off
	v_add_u32_e32 v18, v11, v10
	v_ashrrev_i32_e32 v19, 31, v18
	v_mad_i64_i32 v[66:67], s[0:1], v18, s4, v[58:59]
	v_lshlrev_b64 v[14:15], 9, v[18:19]
	v_mad_i64_i32 v[18:19], s[0:1], v18, s87, v[62:63]
	v_lshl_add_u64 v[14:15], v[60:61], 0, v[14:15]
	global_load_dwordx4 v[10:13], v[66:67], off
	v_add_u32_e32 v84, 0x800, v84
	global_load_dwordx4 v[14:17], v[14:15], off
	s_waitcnt vmcnt(10)
	v_lshlrev_b32_e32 v72, 16, v49
	v_and_b32_e32 v73, 0xffff0000, v49
	s_waitcnt vmcnt(9)
	v_lshlrev_b32_e32 v74, 16, v53
	v_and_b32_e32 v75, 0xffff0000, v53
	s_waitcnt vmcnt(8)
	v_lshlrev_b32_e32 v78, 16, v57
	v_and_b32_e32 v79, 0xffff0000, v57
	v_lshlrev_b32_e32 v57, 16, v56
	v_and_b32_e32 v56, 0xffff0000, v56
	v_pk_add_f32 v[72:73], v[72:73], v[74:75]
	v_lshlrev_b32_e32 v74, 16, v48
	v_and_b32_e32 v75, 0xffff0000, v48
	v_lshlrev_b32_e32 v48, 16, v52
	v_and_b32_e32 v49, 0xffff0000, v52
	v_mul_f32_e32 v52, 0xbfb8aa3b, v57
	v_mul_f32_e32 v53, 0xbfb8aa3b, v56
	v_exp_f32_e32 v52, v52
	v_exp_f32_e32 v53, v53
	v_pk_add_f32 v[48:49], v[74:75], v[48:49]
	v_pk_mul_f32 v[80:81], v[72:73], v[72:73]
	v_pk_mul_f32 v[82:83], v[48:49], v[48:49]
	v_pk_add_f32 v[52:53], v[52:53], 1.0 op_sel_hi:[1,0]
	global_load_dwordx4 v[18:21], v[18:19], off
	v_div_scale_f32 v74, s[0:1], v53, v53, v56
	v_rcp_f32_e32 v75, v74
	s_nop 0
	v_fma_f32 v76, -v74, v75, 1.0
	v_fmac_f32_e32 v75, v76, v75
	v_div_scale_f32 v76, vcc, v56, v53, v56
	v_mul_f32_e32 v77, v76, v75
	v_fma_f32 v87, -v74, v77, v76
	v_fmac_f32_e32 v77, v87, v75
	v_fma_f32 v74, -v74, v77, v76
	v_div_fmas_f32 v74, v74, v75, v77
	v_div_fixup_f32 v53, v74, v53, v56
	v_div_scale_f32 v56, s[0:1], v52, v52, v57
	v_rcp_f32_e32 v74, v56
	s_nop 0
	v_fma_f32 v75, -v56, v74, 1.0
	v_fmac_f32_e32 v74, v75, v74
	v_div_scale_f32 v75, vcc, v57, v52, v57
	v_mul_f32_e32 v76, v75, v74
	v_fma_f32 v77, -v56, v76, v75
	v_fmac_f32_e32 v76, v77, v74
	v_fma_f32 v56, -v56, v76, v75
	v_div_fmas_f32 v56, v56, v74, v76
	v_div_fixup_f32 v52, v56, v52, v57
	v_lshlrev_b32_e32 v56, 16, v47
	v_and_b32_e32 v57, 0xffff0000, v47
	v_lshlrev_b32_e32 v47, 16, v55
	v_lshlrev_b32_e32 v74, 16, v51
	v_and_b32_e32 v75, 0xffff0000, v51
	v_and_b32_e32 v51, 0xffff0000, v55
	v_mul_f32_e32 v55, 0xbfb8aa3b, v47
	v_pk_add_f32 v[56:57], v[56:57], v[74:75]
	v_exp_f32_e32 v74, v55
	v_mul_f32_e32 v55, 0xbfb8aa3b, v51
	v_exp_f32_e32 v75, v55
	v_pk_mul_f32 v[90:91], v[56:57], v[56:57]
	v_pk_add_f32 v[74:75], v[74:75], 1.0 op_sel_hi:[1,0]
	s_nop 0
	v_div_scale_f32 v55, s[0:1], v75, v75, v51
	v_rcp_f32_e32 v76, v55
	s_nop 0
	v_fma_f32 v77, -v55, v76, 1.0
	v_fmac_f32_e32 v76, v77, v76
	v_div_scale_f32 v77, vcc, v51, v75, v51
	v_mul_f32_e32 v87, v77, v76
	v_fma_f32 v88, -v55, v87, v77
	v_fmac_f32_e32 v87, v88, v76
	v_fma_f32 v55, -v55, v87, v77
	v_div_fmas_f32 v55, v55, v76, v87
	v_div_fixup_f32 v75, v55, v75, v51
	v_div_scale_f32 v51, s[0:1], v74, v74, v47
	v_rcp_f32_e32 v55, v51
	s_nop 0
	v_fma_f32 v76, -v51, v55, 1.0
	v_fmac_f32_e32 v55, v76, v55
	v_div_scale_f32 v76, vcc, v47, v74, v47
	v_mul_f32_e32 v77, v76, v55
	v_fma_f32 v87, -v51, v77, v76
	v_fmac_f32_e32 v77, v87, v55
	v_fma_f32 v51, -v51, v77, v76
	v_div_fmas_f32 v51, v51, v55, v77
	v_lshlrev_b32_e32 v55, 16, v54
	v_and_b32_e32 v54, 0xffff0000, v54
	v_div_fixup_f32 v74, v51, v74, v47
	v_lshlrev_b32_e32 v76, 16, v46
	v_and_b32_e32 v77, 0xffff0000, v46
	v_lshlrev_b32_e32 v46, 16, v50
	v_and_b32_e32 v47, 0xffff0000, v50
	v_mul_f32_e32 v50, 0xbfb8aa3b, v55
	v_mul_f32_e32 v51, 0xbfb8aa3b, v54
	v_exp_f32_e32 v50, v50
	v_exp_f32_e32 v51, v51
	v_pk_add_f32 v[46:47], v[76:77], v[46:47]
	v_pk_add_f32 v[50:51], v[50:51], 1.0 op_sel_hi:[1,0]
	s_nop 0
	v_div_scale_f32 v76, s[0:1], v51, v51, v54
	v_rcp_f32_e32 v77, v76
	v_pk_mul_f32 v[92:93], v[46:47], v[46:47]
	v_fma_f32 v87, -v76, v77, 1.0
	v_fmac_f32_e32 v77, v87, v77
	v_div_scale_f32 v87, vcc, v54, v51, v54
	v_mul_f32_e32 v88, v87, v77
	v_fma_f32 v89, -v76, v88, v87
; DI float siluf(float x) { return x / (1.f + __expf(-x)); }
; DI void pair_finalize(const Params& p, int layer, int kind, int b, int hh) {
;     ...
;     for (int u = 0; u < 4; ++u) {
;       const int rr = (ltid + 512 * (j0 + u)) >> 3;
;       const int row = rr < TT ? b * TT + rr : NLAT + b * LC + (rr - TT);
;       float fa[8], fb[8], fz[8], o[8];
;       unpack8(a[u], fa); unpack8(bw[u], fb); unpack8(z[u], fz);
;       float sm = 0.f;
; #pragma unroll
;       for (int e = 0; e < 8; ++e) { o[e] = fa[e] + fb[e]; sm += o[e]; }
;       sm += __shfl_xor(sm, 1); sm += __shfl_xor(sm, 2); sm += __shfl_xor(sm, 4);
;       const float mean = kind ? sm * (1.f / 64.f) : 0.f;
;       float ss = 0.f;
; #pragma unroll
;       for (int e = 0; e < 8; ++e) { o[e] -= mean; ss += o[e] * o[e]; }
;       ss += __shfl_xor(ss, 1); ss += __shfl_xor(ss, 2); ss += __shfl_xor(ss, 4);
;       const float rn = rsqrtf(ss * (1.f / 64.f) + 1e-6f);
; #pragma unroll
;       for (int e = 0; e < 8; ++e) o[e] = o[e] * rn * gg[e] * siluf(fz[e]);
	v_fmac_f32_e32 v88, v89, v77
	v_fma_f32 v76, -v76, v88, v87
	v_div_fmas_f32 v76, v76, v77, v88
	v_div_fixup_f32 v51, v76, v51, v54
	v_div_scale_f32 v54, s[0:1], v50, v50, v55
	v_rcp_f32_e32 v76, v54
	s_nop 0
	v_fma_f32 v77, -v54, v76, 1.0
	v_fmac_f32_e32 v76, v77, v76
	v_div_scale_f32 v77, vcc, v55, v50, v55
	v_mul_f32_e32 v87, v77, v76
	v_fma_f32 v88, -v54, v87, v77
	v_fmac_f32_e32 v87, v88, v76
	v_fma_f32 v54, -v54, v87, v77
	v_div_fmas_f32 v54, v54, v76, v87
	v_div_fixup_f32 v50, v54, v50, v55
	v_mul_f32_e32 v54, 0xbfb8aa3b, v78
	v_mul_f32_e32 v55, 0xbfb8aa3b, v79
	v_exp_f32_e32 v54, v54
	v_exp_f32_e32 v55, v55
	s_nop 0
	v_pk_add_f32 v[54:55], v[54:55], 1.0 op_sel_hi:[1,0]
	s_nop 0
	v_div_scale_f32 v76, s[0:1], v55, v55, v79
	v_rcp_f32_e32 v77, v76
	s_nop 0
	v_fma_f32 v87, -v76, v77, 1.0
	v_fmac_f32_e32 v77, v87, v77
	v_div_scale_f32 v87, vcc, v79, v55, v79
	v_mul_f32_e32 v88, v87, v77
	v_fma_f32 v89, -v76, v88, v87
	v_fmac_f32_e32 v88, v89, v77
	v_fma_f32 v76, -v76, v88, v87
	v_div_fmas_f32 v76, v76, v77, v88
	v_div_fixup_f32 v77, v76, v55, v79
	v_div_scale_f32 v55, s[0:1], v54, v54, v78
	v_rcp_f32_e32 v76, v55
	s_nop 0
	v_fma_f32 v79, -v55, v76, 1.0
	v_fmac_f32_e32 v76, v79, v76
	v_div_scale_f32 v79, vcc, v78, v54, v78
	v_mul_f32_e32 v87, v79, v76
	v_fma_f32 v88, -v55, v87, v79
	v_fmac_f32_e32 v87, v88, v76
	v_fma_f32 v55, -v55, v87, v79
	v_div_fmas_f32 v55, v55, v76, v87
	v_div_fixup_f32 v76, v55, v54, v78
	s_waitcnt vmcnt(5)
	v_lshlrev_b32_e32 v54, 16, v37
	v_and_b32_e32 v55, 0xffff0000, v37
	v_lshlrev_b32_e32 v78, 16, v41
	v_and_b32_e32 v79, 0xffff0000, v41
	v_lshlrev_b32_e32 v87, 16, v45
	v_and_b32_e32 v88, 0xffff0000, v45
	v_lshlrev_b32_e32 v45, 16, v44
	v_and_b32_e32 v44, 0xffff0000, v44
	v_pk_add_f32 v[54:55], v[54:55], v[78:79]
	v_lshlrev_b32_e32 v78, 16, v36
	v_and_b32_e32 v79, 0xffff0000, v36
	v_lshlrev_b32_e32 v36, 16, v40
	v_and_b32_e32 v37, 0xffff0000, v40
	v_mul_f32_e32 v40, 0xbfb8aa3b, v45
	v_mul_f32_e32 v41, 0xbfb8aa3b, v44
	v_exp_f32_e32 v40, v40
	v_exp_f32_e32 v41, v41
	v_pk_add_f32 v[36:37], v[78:79], v[36:37]
	v_pk_mul_f32 v[94:95], v[54:55], v[54:55]
	v_pk_mul_f32 v[96:97], v[36:37], v[36:37]
	v_pk_add_f32 v[40:41], v[40:41], 1.0 op_sel_hi:[1,0]
	s_nop 0
	v_div_scale_f32 v78, s[0:1], v41, v41, v44
	v_rcp_f32_e32 v79, v78
	s_nop 0
	v_fma_f32 v89, -v78, v79, 1.0
	v_fmac_f32_e32 v79, v89, v79
	v_div_scale_f32 v89, vcc, v44, v41, v44
	v_mul_f32_e32 v98, v89, v79
	v_fma_f32 v99, -v78, v98, v89
	v_fmac_f32_e32 v98, v99, v79
	v_fma_f32 v78, -v78, v98, v89
	v_div_fmas_f32 v78, v78, v79, v98
	v_div_fixup_f32 v41, v78, v41, v44
	v_div_scale_f32 v44, s[0:1], v40, v40, v45
	v_rcp_f32_e32 v78, v44
	s_nop 0
	v_fma_f32 v79, -v44, v78, 1.0
	v_fmac_f32_e32 v78, v79, v78
	v_div_scale_f32 v79, vcc, v45, v40, v45
	v_mul_f32_e32 v89, v79, v78
	v_fma_f32 v98, -v44, v89, v79
	v_fmac_f32_e32 v89, v98, v78
	v_fma_f32 v44, -v44, v89, v79
	v_div_fmas_f32 v44, v44, v78, v89
	v_div_fixup_f32 v40, v44, v40, v45
	v_lshlrev_b32_e32 v44, 16, v35
	v_and_b32_e32 v45, 0xffff0000, v35
	v_lshlrev_b32_e32 v35, 16, v43
	v_lshlrev_b32_e32 v78, 16, v39
	v_and_b32_e32 v79, 0xffff0000, v39
	v_and_b32_e32 v39, 0xffff0000, v43
	v_mul_f32_e32 v43, 0xbfb8aa3b, v35
	v_pk_add_f32 v[44:45], v[44:45], v[78:79]
	v_exp_f32_e32 v78, v43
	v_mul_f32_e32 v43, 0xbfb8aa3b, v39
	v_exp_f32_e32 v79, v43
	v_pk_mul_f32 v[98:99], v[44:45], v[44:45]
	v_pk_add_f32 v[78:79], v[78:79], 1.0 op_sel_hi:[1,0]
	s_nop 0
	v_div_scale_f32 v43, s[0:1], v79, v79, v39
	v_rcp_f32_e32 v89, v43
	s_nop 0
	v_fma_f32 v100, -v43, v89, 1.0
	v_fmac_f32_e32 v89, v100, v89
	v_div_scale_f32 v100, vcc, v39, v79, v39
	v_mul_f32_e32 v101, v100, v89
	v_fma_f32 v102, -v43, v101, v100
	v_fmac_f32_e32 v101, v102, v89
	v_fma_f32 v43, -v43, v101, v100
	v_div_fmas_f32 v43, v43, v89, v101
	v_div_fixup_f32 v79, v43, v79, v39
	v_div_scale_f32 v39, s[0:1], v78, v78, v35
	v_rcp_f32_e32 v43, v39
	v_and_b32_e32 v102, 0xffff0000, v42
	v_fma_f32 v89, -v39, v43, 1.0
	v_fmac_f32_e32 v43, v89, v43
	v_div_scale_f32 v89, vcc, v35, v78, v35
	v_mul_f32_e32 v100, v89, v43
	v_fma_f32 v101, -v39, v100, v89
	v_fmac_f32_e32 v100, v101, v43
	v_fma_f32 v39, -v39, v100, v89
	v_div_fmas_f32 v39, v39, v43, v100
	v_div_fixup_f32 v78, v39, v78, v35
	v_lshlrev_b32_e32 v100, 16, v34
	v_and_b32_e32 v101, 0xffff0000, v34
	v_lshlrev_b32_e32 v34, 16, v38
	v_and_b32_e32 v35, 0xffff0000, v38
	v_pk_add_f32 v[34:35], v[100:101], v[34:35]
	v_lshlrev_b32_e32 v89, 16, v42
	v_pk_mul_f32 v[38:39], v[34:35], v[34:35]
	v_mov_b32_e32 v43, v92
	v_mov_b32_e32 v42, v38
	v_mov_b32_e32 v92, v39
	v_mul_f32_e32 v38, 0xbfb8aa3b, v89
	v_mul_f32_e32 v39, 0xbfb8aa3b, v102
	v_exp_f32_e32 v38, v38
	v_exp_f32_e32 v39, v39
	v_pk_add_f32 v[42:43], v[42:43], v[92:93]
	v_pk_add_f32 v[38:39], v[38:39], 1.0 op_sel_hi:[1,0]
	s_nop 0
	v_div_scale_f32 v92, s[0:1], v39, v39, v102
	v_rcp_f32_e32 v93, v92
	s_nop 0
	v_fma_f32 v100, -v92, v93, 1.0
	v_fmac_f32_e32 v93, v100, v93
	v_div_scale_f32 v100, vcc, v102, v39, v102
	v_mul_f32_e32 v101, v100, v93
	v_fma_f32 v103, -v92, v101, v100
	v_fmac_f32_e32 v101, v103, v93
	v_fma_f32 v92, -v92, v101, v100
	v_div_fmas_f32 v92, v92, v93, v101
	v_div_fixup_f32 v39, v92, v39, v102
	v_div_scale_f32 v92, s[0:1], v38, v38, v89
	v_rcp_f32_e32 v93, v92
	s_nop 0
	v_fma_f32 v100, -v92, v93, 1.0
	v_fmac_f32_e32 v93, v100, v93
	v_div_scale_f32 v100, vcc, v89, v38, v89
	v_mul_f32_e32 v101, v100, v93
	v_fma_f32 v102, -v92, v101, v100
	v_fmac_f32_e32 v101, v102, v93
	v_fma_f32 v92, -v92, v101, v100
	v_div_fmas_f32 v92, v92, v93, v101
	v_div_fixup_f32 v38, v92, v38, v89
	v_mov_b32_e32 v92, v98
	v_mov_b32_e32 v93, v90
	v_pk_add_f32 v[42:43], v[92:93], v[42:43]
	v_mov_b32_e32 v90, v99
	v_pk_add_f32 v[42:43], v[90:91], v[42:43]
	v_mov_b32_e32 v90, v96
	v_mov_b32_e32 v91, v82
	v_pk_add_f32 v[42:43], v[90:91], v[42:43]
	v_mov_b32_e32 v82, v97
	v_pk_add_f32 v[42:43], v[82:83], v[42:43]
	v_mov_b32_e32 v82, v94
	v_mov_b32_e32 v83, v80
	v_pk_add_f32 v[42:43], v[82:83], v[42:43]
	v_mov_b32_e32 v80, v95
	v_pk_add_f32 v[42:43], v[80:81], v[42:43]
	s_nop 1
	v_add_f32_dpp v42, v42, v42 quad_perm:[1,0,3,2] row_mask:0xf bank_mask:0xf
	s_waitcnt lgkmcnt(0)
; DI float siluf(float x) { return x / (1.f + __expf(-x)); }
; DI void pair_finalize(const Params& p, int layer, int kind, int b, int hh) {
;     ...
;       sm += __shfl_xor(sm, 1); sm += __shfl_xor(sm, 2); sm += __shfl_xor(sm, 4);
;       const float mean = kind ? sm * (1.f / 64.f) : 0.f;
;       float ss = 0.f;
; #pragma unroll
;       for (int e = 0; e < 8; ++e) { o[e] -= mean; ss += o[e] * o[e]; }
;       ss += __shfl_xor(ss, 1); ss += __shfl_xor(ss, 2); ss += __shfl_xor(ss, 4);
;       const float rn = rsqrtf(ss * (1.f / 64.f) + 1e-6f);
; #pragma unroll
;       for (int e = 0; e < 8; ++e) o[e] = o[e] * rn * gg[e] * siluf(fz[e]);
;       *(u32x4*)(act + (size_t)row * AP + acol + c8 * 8) = pack8(o);
	v_add_f32_dpp v43, v43, v43 quad_perm:[1,0,3,2] row_mask:0xf bank_mask:0xf
	s_nop 1
	v_add_f32_dpp v42, v42, v42 quad_perm:[2,3,0,1] row_mask:0xf bank_mask:0xf
	s_waitcnt lgkmcnt(0)
	v_add_f32_dpp v43, v43, v43 quad_perm:[2,3,0,1] row_mask:0xf bank_mask:0xf
	s_nop 1
	v_add_f32_dpp v42, v42, v42 row_half_mirror row_mask:0xf bank_mask:0xf
	s_waitcnt lgkmcnt(0)
	v_add_f32_dpp v43, v43, v43 row_half_mirror row_mask:0xf bank_mask:0xf
	v_mov_b64_e32 v[80:81], s[8:9]
	v_pk_fma_f32 v[42:43], v[42:43], s[10:11], v[80:81] op_sel_hi:[1,0,0]
	s_nop 0
	v_mul_f32_e32 v82, 0x4b800000, v43
	v_cmp_gt_f32_e64 s[0:1], s6, v43
	v_cmp_gt_f32_e32 vcc, s6, v42
	s_nop 0
	v_cndmask_b32_e64 v43, v43, v82, s[0:1]
	v_rsq_f32_e32 v43, v43
	s_nop 0
	v_mul_f32_e32 v82, 0x45800000, v43
	v_cndmask_b32_e64 v82, v43, v82, s[0:1]
	v_mul_f32_e32 v43, 0x4b800000, v42
	v_cndmask_b32_e32 v42, v42, v43, vcc
	v_rsq_f32_e32 v42, v42
	v_pk_mul_f32 v[46:47], v[46:47], v[82:83] op_sel_hi:[1,0]
	v_pk_mul_f32 v[48:49], v[48:49], v[82:83] op_sel_hi:[1,0]
	v_pk_mul_f32 v[46:47], v[6:7], v[46:47]
	v_mul_f32_e32 v43, 0x45800000, v42
	v_cndmask_b32_e32 v42, v42, v43, vcc
	v_pk_mul_f32 v[36:37], v[36:37], v[42:43] op_sel_hi:[1,0]
	v_pk_mul_f32 v[34:35], v[34:35], v[42:43] op_sel_hi:[1,0]
	v_pk_mul_f32 v[36:37], v[2:3], v[36:37]
	v_pk_mul_f32 v[34:35], v[6:7], v[34:35]
	v_pk_mul_f32 v[36:37], v[40:41], v[36:37]
	v_mul_f32_e32 v40, 0xbfb8aa3b, v87
	v_mul_f32_e32 v41, 0xbfb8aa3b, v88
	v_exp_f32_e32 v40, v40
	v_exp_f32_e32 v41, v41
	v_pk_mul_f32 v[48:49], v[2:3], v[48:49]
	v_pk_mul_f32 v[34:35], v[38:39], v[34:35]
	v_pk_mul_f32 v[38:39], v[44:45], v[42:43] op_sel_hi:[1,0]
	v_pk_add_f32 v[40:41], v[40:41], 1.0 op_sel_hi:[1,0]
	v_pk_mul_f32 v[46:47], v[50:51], v[46:47]
	v_div_scale_f32 v44, s[0:1], v41, v41, v88
	v_pk_mul_f32 v[50:51], v[56:57], v[82:83] op_sel_hi:[1,0]
	v_pk_mul_f32 v[48:49], v[52:53], v[48:49]
	v_pk_mul_f32 v[52:53], v[72:73], v[82:83] op_sel_hi:[1,0]
	v_rcp_f32_e32 v45, v44
	v_pk_mul_f32 v[50:51], v[8:9], v[50:51]
	v_pk_mul_f32 v[52:53], v[4:5], v[52:53]
	v_pk_mul_f32 v[50:51], v[74:75], v[50:51]
	v_pk_mul_f32 v[52:53], v[76:77], v[52:53]
	v_cvt_pk_bf16_f32 v46, v46, v47
	v_cvt_pk_bf16_f32 v47, v50, v51
	v_cvt_pk_bf16_f32 v48, v48, v49
	v_cvt_pk_bf16_f32 v49, v52, v53
	global_store_dwordx4 v[68:69], v[46:49], off
	v_pk_mul_f32 v[42:43], v[54:55], v[42:43] op_sel_hi:[1,0]
	v_pk_mul_f32 v[38:39], v[8:9], v[38:39]
	v_fma_f32 v46, -v44, v45, 1.0
	v_fmac_f32_e32 v45, v46, v45
	v_div_scale_f32 v46, vcc, v88, v41, v88
	v_mul_f32_e32 v47, v46, v45
	v_fma_f32 v48, -v44, v47, v46
	v_fmac_f32_e32 v47, v48, v45
	v_fma_f32 v44, -v44, v47, v46
	v_div_fmas_f32 v44, v44, v45, v47
	v_div_fixup_f32 v41, v44, v41, v88
	v_div_scale_f32 v44, s[0:1], v40, v40, v87
	v_rcp_f32_e32 v45, v44
	v_pk_mul_f32 v[42:43], v[4:5], v[42:43]
	v_pk_mul_f32 v[38:39], v[78:79], v[38:39]
	v_cvt_pk_bf16_f32 v34, v34, v35
	v_fma_f32 v46, -v44, v45, 1.0
	v_fmac_f32_e32 v45, v46, v45
	v_div_scale_f32 v46, vcc, v87, v40, v87
	v_mul_f32_e32 v47, v46, v45
	v_fma_f32 v48, -v44, v47, v46
	v_fmac_f32_e32 v47, v48, v45
	v_fma_f32 v44, -v44, v47, v46
	v_div_fmas_f32 v44, v44, v45, v47
	v_div_fixup_f32 v40, v44, v40, v87
	v_pk_mul_f32 v[40:41], v[40:41], v[42:43]
	v_cvt_pk_bf16_f32 v35, v38, v39
	v_cvt_pk_bf16_f32 v36, v36, v37
	v_cvt_pk_bf16_f32 v37, v40, v41
	v_lshlrev_b32_e32 v40, 16, v32
	v_and_b32_e32 v41, 0xffff0000, v32
	global_store_dwordx4 v[70:71], v[34:37], off
	s_waitcnt vmcnt(6)
	v_lshlrev_b32_e32 v38, 16, v24
	v_and_b32_e32 v39, 0xffff0000, v24
	v_lshlrev_b32_e32 v34, 16, v25
	v_and_b32_e32 v35, 0xffff0000, v25
	s_waitcnt vmcnt(5)
	v_lshlrev_b32_e32 v36, 16, v29
	v_and_b32_e32 v37, 0xffff0000, v29
	v_lshlrev_b32_e32 v24, 16, v28
	v_and_b32_e32 v25, 0xffff0000, v28
	v_mul_f32_e32 v28, 0xbfb8aa3b, v40
	v_mul_f32_e32 v29, 0xbfb8aa3b, v41
	v_exp_f32_e32 v28, v28
	v_exp_f32_e32 v29, v29
	v_pk_add_f32 v[24:25], v[38:39], v[24:25]
	v_lshlrev_b32_e32 v46, 16, v33
	v_and_b32_e32 v47, 0xffff0000, v33
	v_pk_add_f32 v[28:29], v[28:29], 1.0 op_sel_hi:[1,0]
	s_waitcnt vmcnt(2)
	v_and_b32_e32 v53, 0xffff0000, v20
	v_div_scale_f32 v38, s[0:1], v29, v29, v41
	v_rcp_f32_e32 v39, v38
	v_lshlrev_b32_e32 v68, 16, v21
	v_and_b32_e32 v69, 0xffff0000, v21
	v_mul_f32_e32 v21, 0xbfb8aa3b, v53
	v_fma_f32 v42, -v38, v39, 1.0
	v_fmac_f32_e32 v39, v42, v39
	v_div_scale_f32 v42, vcc, v41, v29, v41
	v_mul_f32_e32 v43, v42, v39
	v_fma_f32 v44, -v38, v43, v42
	v_fmac_f32_e32 v43, v44, v39
	v_fma_f32 v38, -v38, v43, v42
	v_div_fmas_f32 v38, v38, v39, v43
	v_div_fixup_f32 v29, v38, v29, v41
	v_div_scale_f32 v38, s[0:1], v28, v28, v40
	v_rcp_f32_e32 v39, v38
	v_exp_f32_e32 v21, v21
	v_pk_mul_f32 v[32:33], v[24:25], v[24:25]
	v_pk_add_f32 v[34:35], v[34:35], v[36:37]
	v_fma_f32 v41, -v38, v39, 1.0
	v_fmac_f32_e32 v39, v41, v39
	v_div_scale_f32 v41, vcc, v40, v28, v40
	v_mul_f32_e32 v42, v41, v39
	v_fma_f32 v43, -v38, v42, v41
	v_fmac_f32_e32 v42, v43, v39
	v_fma_f32 v38, -v38, v42, v41
	v_div_fmas_f32 v38, v38, v39, v42
	v_div_fixup_f32 v28, v38, v28, v40
	v_lshlrev_b32_e32 v38, 16, v23
	v_and_b32_e32 v39, 0xffff0000, v23
	v_lshlrev_b32_e32 v23, 16, v31
	v_lshlrev_b32_e32 v40, 16, v27
	v_and_b32_e32 v41, 0xffff0000, v27
	v_and_b32_e32 v27, 0xffff0000, v31
	v_mul_f32_e32 v31, 0xbfb8aa3b, v23
	v_exp_f32_e32 v42, v31
	v_mul_f32_e32 v31, 0xbfb8aa3b, v27
	v_exp_f32_e32 v43, v31
	v_pk_add_f32 v[38:39], v[38:39], v[40:41]
	v_pk_mul_f32 v[36:37], v[34:35], v[34:35]
	v_pk_mul_f32 v[40:41], v[38:39], v[38:39]
	v_pk_add_f32 v[42:43], v[42:43], 1.0 op_sel_hi:[1,0]
	s_nop 0
	v_div_scale_f32 v31, s[0:1], v43, v43, v27
	v_rcp_f32_e32 v44, v31
	s_nop 0
; DI float siluf(float x) { return x / (1.f + __expf(-x)); }
; DI void pair_finalize(const Params& p, int layer, int kind, int b, int hh) {
;     ...
;     for (int u = 0; u < 4; ++u) {
;       const int rr = (ltid + 512 * (j0 + u)) >> 3;
;       const int row = rr < TT ? b * TT + rr : NLAT + b * LC + (rr - TT);
;       float fa[8], fb[8], fz[8], o[8];
;       unpack8(a[u], fa); unpack8(bw[u], fb); unpack8(z[u], fz);
;       float sm = 0.f;
; #pragma unroll
;       for (int e = 0; e < 8; ++e) { o[e] = fa[e] + fb[e]; sm += o[e]; }
;       sm += __shfl_xor(sm, 1); sm += __shfl_xor(sm, 2); sm += __shfl_xor(sm, 4);
;       const float mean = kind ? sm * (1.f / 64.f) : 0.f;
;       float ss = 0.f;
; #pragma unroll
;       for (int e = 0; e < 8; ++e) { o[e] -= mean; ss += o[e] * o[e]; }
;       ss += __shfl_xor(ss, 1); ss += __shfl_xor(ss, 2); ss += __shfl_xor(ss, 4);
;       const float rn = rsqrtf(ss * (1.f / 64.f) + 1e-6f);
; #pragma unroll
;       for (int e = 0; e < 8; ++e) o[e] = o[e] * rn * gg[e] * siluf(fz[e]);
	v_fma_f32 v45, -v31, v44, 1.0
	v_fmac_f32_e32 v44, v45, v44
	v_div_scale_f32 v45, vcc, v27, v43, v27
	v_mul_f32_e32 v48, v45, v44
	v_fma_f32 v49, -v31, v48, v45
	v_fmac_f32_e32 v48, v49, v44
	v_fma_f32 v31, -v31, v48, v45
	v_div_fmas_f32 v31, v31, v44, v48
	v_div_fixup_f32 v43, v31, v43, v27
	v_div_scale_f32 v27, s[0:1], v42, v42, v23
	v_rcp_f32_e32 v31, v27
	v_and_b32_e32 v49, 0xffff0000, v30
	v_fma_f32 v44, -v27, v31, 1.0
	v_fmac_f32_e32 v31, v44, v31
	v_div_scale_f32 v44, vcc, v23, v42, v23
	v_mul_f32_e32 v45, v44, v31
	v_fma_f32 v48, -v27, v45, v44
	v_fmac_f32_e32 v45, v48, v31
	v_fma_f32 v27, -v27, v45, v44
	v_lshlrev_b32_e32 v48, 16, v30
	v_div_fmas_f32 v27, v27, v31, v45
	v_mul_f32_e32 v30, 0xbfb8aa3b, v48
	v_mul_f32_e32 v31, 0xbfb8aa3b, v49
	v_exp_f32_e32 v30, v30
	v_exp_f32_e32 v31, v31
	v_div_fixup_f32 v42, v27, v42, v23
	v_lshlrev_b32_e32 v44, 16, v22
	v_and_b32_e32 v45, 0xffff0000, v22
	v_lshlrev_b32_e32 v22, 16, v26
	v_and_b32_e32 v23, 0xffff0000, v26
	v_pk_add_f32 v[30:31], v[30:31], 1.0 op_sel_hi:[1,0]
	v_pk_add_f32 v[22:23], v[44:45], v[22:23]
	v_div_scale_f32 v44, s[0:1], v31, v31, v49
	v_rcp_f32_e32 v45, v44
	v_pk_mul_f32 v[26:27], v[22:23], v[22:23]
	v_fma_f32 v50, -v44, v45, 1.0
	v_fmac_f32_e32 v45, v50, v45
	v_div_scale_f32 v50, vcc, v49, v31, v49
	v_mul_f32_e32 v51, v50, v45
	v_fma_f32 v52, -v44, v51, v50
	v_fmac_f32_e32 v51, v52, v45
	v_fma_f32 v44, -v44, v51, v50
	v_div_fmas_f32 v44, v44, v45, v51
	v_div_fixup_f32 v31, v44, v31, v49
	v_div_scale_f32 v44, s[0:1], v30, v30, v48
	v_rcp_f32_e32 v45, v44
	s_nop 0
	v_fma_f32 v49, -v44, v45, 1.0
	v_fmac_f32_e32 v45, v49, v45
	v_div_scale_f32 v49, vcc, v48, v30, v48
	v_mul_f32_e32 v50, v49, v45
	v_fma_f32 v51, -v44, v50, v49
	v_fmac_f32_e32 v50, v51, v45
	v_fma_f32 v44, -v44, v50, v49
	v_div_fmas_f32 v44, v44, v45, v50
	v_div_fixup_f32 v30, v44, v30, v48
	v_mul_f32_e32 v44, 0xbfb8aa3b, v46
	v_mul_f32_e32 v45, 0xbfb8aa3b, v47
	v_exp_f32_e32 v44, v44
	v_exp_f32_e32 v45, v45
	s_nop 0
	v_pk_add_f32 v[44:45], v[44:45], 1.0 op_sel_hi:[1,0]
	s_nop 0
	v_div_scale_f32 v48, s[0:1], v45, v45, v47
	v_rcp_f32_e32 v49, v48
	s_nop 0
	v_fma_f32 v50, -v48, v49, 1.0
	v_fmac_f32_e32 v49, v50, v49
	v_div_scale_f32 v50, vcc, v47, v45, v47
	v_mul_f32_e32 v51, v50, v49
	v_fma_f32 v52, -v48, v51, v50
	v_fmac_f32_e32 v51, v52, v49
	v_fma_f32 v48, -v48, v51, v50
	v_div_fmas_f32 v48, v48, v49, v51
	v_div_fixup_f32 v45, v48, v45, v47
	v_div_scale_f32 v47, s[0:1], v44, v44, v46
	v_rcp_f32_e32 v48, v47
	v_lshlrev_b32_e32 v52, 16, v20
	v_mul_f32_e32 v20, 0xbfb8aa3b, v52
	v_exp_f32_e32 v20, v20
	v_fma_f32 v49, -v47, v48, 1.0
	v_fmac_f32_e32 v48, v49, v48
	v_div_scale_f32 v49, vcc, v46, v44, v46
	v_mul_f32_e32 v50, v49, v48
	v_fma_f32 v51, -v47, v50, v49
	v_fmac_f32_e32 v50, v51, v48
	v_fma_f32 v47, -v47, v50, v49
	v_div_fmas_f32 v47, v47, v48, v50
	v_div_fixup_f32 v44, v47, v44, v46
	v_lshlrev_b32_e32 v46, 16, v13
	v_and_b32_e32 v47, 0xffff0000, v13
	v_lshlrev_b32_e32 v50, 16, v12
	v_and_b32_e32 v51, 0xffff0000, v12
	v_lshlrev_b32_e32 v12, 16, v16
	v_and_b32_e32 v13, 0xffff0000, v16
	v_pk_add_f32 v[20:21], v[20:21], 1.0 op_sel_hi:[1,0]
	v_lshlrev_b32_e32 v48, 16, v17
	v_and_b32_e32 v49, 0xffff0000, v17
	v_pk_add_f32 v[16:17], v[50:51], v[12:13]
	v_div_scale_f32 v50, s[0:1], v21, v21, v53
	v_rcp_f32_e32 v51, v50
	v_pk_mul_f32 v[12:13], v[16:17], v[16:17]
	v_pk_add_f32 v[46:47], v[46:47], v[48:49]
	v_fma_f32 v54, -v50, v51, 1.0
	v_fmac_f32_e32 v51, v54, v51
	v_div_scale_f32 v54, vcc, v53, v21, v53
	v_mul_f32_e32 v55, v54, v51
	v_fma_f32 v56, -v50, v55, v54
	v_fmac_f32_e32 v55, v56, v51
	v_fma_f32 v50, -v50, v55, v54
	v_div_fmas_f32 v50, v50, v51, v55
	v_div_fixup_f32 v21, v50, v21, v53
	v_div_scale_f32 v50, s[0:1], v20, v20, v52
	v_rcp_f32_e32 v51, v50
	v_pk_mul_f32 v[48:49], v[46:47], v[46:47]
	v_fma_f32 v53, -v50, v51, 1.0
	v_fmac_f32_e32 v51, v53, v51
	v_div_scale_f32 v53, vcc, v52, v20, v52
	v_mul_f32_e32 v54, v53, v51
	v_fma_f32 v55, -v50, v54, v53
	v_fmac_f32_e32 v54, v55, v51
	v_fma_f32 v50, -v50, v54, v53
	v_div_fmas_f32 v50, v50, v51, v54
	v_div_fixup_f32 v20, v50, v20, v52
	v_lshlrev_b32_e32 v50, 16, v11
	v_and_b32_e32 v51, 0xffff0000, v11
	v_lshlrev_b32_e32 v11, 16, v19
	v_lshlrev_b32_e32 v52, 16, v15
	v_and_b32_e32 v53, 0xffff0000, v15
	v_and_b32_e32 v15, 0xffff0000, v19
	v_mul_f32_e32 v19, 0xbfb8aa3b, v11
	v_exp_f32_e32 v54, v19
	v_mul_f32_e32 v19, 0xbfb8aa3b, v15
	v_exp_f32_e32 v55, v19
	v_pk_add_f32 v[50:51], v[50:51], v[52:53]
	v_pk_add_f32 v[54:55], v[54:55], 1.0 op_sel_hi:[1,0]
	s_nop 0
	v_div_scale_f32 v19, s[0:1], v55, v55, v15
	v_rcp_f32_e32 v56, v19
	v_pk_mul_f32 v[52:53], v[50:51], v[50:51]
	v_fma_f32 v57, -v19, v56, 1.0
	v_fmac_f32_e32 v56, v57, v56
	v_div_scale_f32 v57, vcc, v15, v55, v15
	v_mul_f32_e32 v70, v57, v56
	v_fma_f32 v71, -v19, v70, v57
	v_fmac_f32_e32 v70, v71, v56
	v_fma_f32 v19, -v19, v70, v57
	v_div_fmas_f32 v19, v19, v56, v70
	v_div_fixup_f32 v55, v19, v55, v15
	v_div_scale_f32 v15, s[0:1], v54, v54, v11
	v_rcp_f32_e32 v19, v15
	v_and_b32_e32 v71, 0xffff0000, v18
	v_fma_f32 v56, -v15, v19, 1.0
	v_fmac_f32_e32 v19, v56, v19
	v_div_scale_f32 v56, vcc, v11, v54, v11
	v_mul_f32_e32 v57, v56, v19
	v_fma_f32 v70, -v15, v57, v56
	v_fmac_f32_e32 v57, v70, v19
	v_fma_f32 v15, -v15, v57, v56
	v_div_fmas_f32 v15, v15, v19, v57
	v_div_fixup_f32 v54, v15, v54, v11
; DI float siluf(float x) { return x / (1.f + __expf(-x)); }
; DI void pair_finalize(const Params& p, int layer, int kind, int b, int hh) {
;     ...
;     for (int u = 0; u < 4; ++u) {
;       const int rr = (ltid + 512 * (j0 + u)) >> 3;
;       const int row = rr < TT ? b * TT + rr : NLAT + b * LC + (rr - TT);
;       float fa[8], fb[8], fz[8], o[8];
;       unpack8(a[u], fa); unpack8(bw[u], fb); unpack8(z[u], fz);
;       float sm = 0.f;
; #pragma unroll
;       for (int e = 0; e < 8; ++e) { o[e] = fa[e] + fb[e]; sm += o[e]; }
;       sm += __shfl_xor(sm, 1); sm += __shfl_xor(sm, 2); sm += __shfl_xor(sm, 4);
;       const float mean = kind ? sm * (1.f / 64.f) : 0.f;
;       float ss = 0.f;
; #pragma unroll
;       for (int e = 0; e < 8; ++e) { o[e] -= mean; ss += o[e] * o[e]; }
;       ss += __shfl_xor(ss, 1); ss += __shfl_xor(ss, 2); ss += __shfl_xor(ss, 4);
;       const float rn = rsqrtf(ss * (1.f / 64.f) + 1e-6f);
; #pragma unroll
;       for (int e = 0; e < 8; ++e) o[e] = o[e] * rn * gg[e] * siluf(fz[e]);
;       *(u32x4*)(act + (size_t)row * AP + acol + c8 * 8) = pack8(o);
;     }
;   }
	v_lshlrev_b32_e32 v56, 16, v10
	v_and_b32_e32 v57, 0xffff0000, v10
	v_lshlrev_b32_e32 v10, 16, v14
	v_and_b32_e32 v11, 0xffff0000, v14
	v_pk_add_f32 v[14:15], v[56:57], v[10:11]
	v_lshlrev_b32_e32 v70, 16, v18
	v_pk_mul_f32 v[10:11], v[14:15], v[14:15]
	v_mov_b32_e32 v19, v26
	v_mov_b32_e32 v18, v10
	v_mov_b32_e32 v26, v11
	v_pk_add_f32 v[10:11], v[18:19], v[26:27]
	v_mul_f32_e32 v18, 0xbfb8aa3b, v70
	v_mul_f32_e32 v19, 0xbfb8aa3b, v71
	v_exp_f32_e32 v18, v18
	v_exp_f32_e32 v19, v19
	s_nop 0
	v_pk_add_f32 v[18:19], v[18:19], 1.0 op_sel_hi:[1,0]
	s_nop 0
	v_div_scale_f32 v26, s[0:1], v19, v19, v71
	v_rcp_f32_e32 v27, v26
	s_nop 0
	v_fma_f32 v56, -v26, v27, 1.0
	v_fmac_f32_e32 v27, v56, v27
	v_div_scale_f32 v56, vcc, v71, v19, v71
	v_mul_f32_e32 v57, v56, v27
	v_fma_f32 v72, -v26, v57, v56
	v_fmac_f32_e32 v57, v72, v27
	v_fma_f32 v26, -v26, v57, v56
	v_div_fmas_f32 v26, v26, v27, v57
	v_div_fixup_f32 v19, v26, v19, v71
	v_div_scale_f32 v26, s[0:1], v18, v18, v70
	v_rcp_f32_e32 v27, v26
	s_nop 0
	v_fma_f32 v56, -v26, v27, 1.0
	v_fmac_f32_e32 v27, v56, v27
	v_div_scale_f32 v56, vcc, v70, v18, v70
	v_mul_f32_e32 v57, v56, v27
	v_fma_f32 v71, -v26, v57, v56
	v_fmac_f32_e32 v57, v71, v27
	v_fma_f32 v26, -v26, v57, v56
	v_div_fmas_f32 v26, v26, v27, v57
	v_div_fixup_f32 v18, v26, v18, v70
	v_mov_b32_e32 v26, v52
	v_mov_b32_e32 v27, v40
	v_pk_add_f32 v[10:11], v[26:27], v[10:11]
	v_mov_b32_e32 v40, v53
	v_pk_add_f32 v[10:11], v[40:41], v[10:11]
	v_mov_b32_e32 v26, v12
	v_mov_b32_e32 v27, v32
	v_pk_add_f32 v[10:11], v[26:27], v[10:11]
	v_mov_b32_e32 v32, v13
	v_pk_add_f32 v[10:11], v[32:33], v[10:11]
	v_mov_b32_e32 v12, v48
	v_mov_b32_e32 v13, v36
	v_pk_add_f32 v[10:11], v[12:13], v[10:11]
	v_mov_b32_e32 v36, v49
	v_pk_add_f32 v[10:11], v[36:37], v[10:11]
	s_nop 1
	v_add_f32_dpp v10, v10, v10 quad_perm:[1,0,3,2] row_mask:0xf bank_mask:0xf
	s_waitcnt lgkmcnt(0)
	v_add_f32_dpp v11, v11, v11 quad_perm:[1,0,3,2] row_mask:0xf bank_mask:0xf
	s_nop 1
	v_add_f32_dpp v10, v10, v10 quad_perm:[2,3,0,1] row_mask:0xf bank_mask:0xf
	s_waitcnt lgkmcnt(0)
	v_add_f32_dpp v11, v11, v11 quad_perm:[2,3,0,1] row_mask:0xf bank_mask:0xf
	s_nop 1
	v_add_f32_dpp v10, v10, v10 row_half_mirror row_mask:0xf bank_mask:0xf
	s_waitcnt lgkmcnt(0)
	v_add_f32_dpp v11, v11, v11 row_half_mirror row_mask:0xf bank_mask:0xf
	s_nop 0
	v_pk_fma_f32 v[26:27], v[10:11], s[10:11], v[80:81] op_sel_hi:[1,0,0]
	s_nop 0
	v_mul_f32_e32 v10, 0x4b800000, v27
	v_cmp_gt_f32_e64 s[0:1], s6, v27
	v_cmp_gt_f32_e32 vcc, s6, v26
	s_nop 0
	v_cndmask_b32_e64 v10, v27, v10, s[0:1]
	v_rsq_f32_e32 v10, v10
	s_nop 0
	v_mul_f32_e32 v11, 0x45800000, v10
	v_cndmask_b32_e64 v10, v10, v11, s[0:1]
	v_pk_mul_f32 v[12:13], v[22:23], v[10:11] op_sel_hi:[1,0]
	v_pk_mul_f32 v[22:23], v[38:39], v[10:11] op_sel_hi:[1,0]
	v_pk_mul_f32 v[24:25], v[24:25], v[10:11] op_sel_hi:[1,0]
	v_pk_mul_f32 v[10:11], v[34:35], v[10:11] op_sel_hi:[1,0]
	v_pk_mul_f32 v[12:13], v[6:7], v[12:13]
	v_pk_mul_f32 v[22:23], v[8:9], v[22:23]
	v_pk_mul_f32 v[24:25], v[2:3], v[24:25]
	v_pk_mul_f32 v[10:11], v[4:5], v[10:11]
	v_pk_mul_f32 v[12:13], v[30:31], v[12:13]
	v_pk_mul_f32 v[22:23], v[42:43], v[22:23]
	v_pk_mul_f32 v[24:25], v[28:29], v[24:25]
	v_pk_mul_f32 v[28:29], v[44:45], v[10:11]
	v_cvt_pk_bf16_f32 v10, v12, v13
	v_cvt_pk_bf16_f32 v11, v22, v23
	v_cvt_pk_bf16_f32 v12, v24, v25
	v_cvt_pk_bf16_f32 v13, v28, v29
	global_store_dwordx4 v[64:65], v[10:13], off
	s_nop 1
	v_mul_f32_e32 v10, 0x4b800000, v26
	v_cndmask_b32_e32 v10, v26, v10, vcc
	v_rsq_f32_e32 v10, v10
	s_nop 0
	v_mul_f32_e32 v11, 0x45800000, v10
	v_cndmask_b32_e32 v10, v10, v11, vcc
	v_pk_mul_f32 v[12:13], v[14:15], v[10:11] op_sel_hi:[1,0]
	v_pk_mul_f32 v[14:15], v[50:51], v[10:11] op_sel_hi:[1,0]
	v_pk_mul_f32 v[12:13], v[6:7], v[12:13]
	v_pk_mul_f32 v[16:17], v[16:17], v[10:11] op_sel_hi:[1,0]
	v_pk_mul_f32 v[12:13], v[18:19], v[12:13]
	v_mul_f32_e32 v11, 0xbfb8aa3b, v68
	v_mul_f32_e32 v19, 0xbfb8aa3b, v69
	v_exp_f32_e32 v18, v11
	v_exp_f32_e32 v19, v19
	v_pk_mul_f32 v[16:17], v[2:3], v[16:17]
	v_pk_mul_f32 v[10:11], v[46:47], v[10:11] op_sel_hi:[1,0]
	v_pk_mul_f32 v[16:17], v[20:21], v[16:17]
	v_pk_add_f32 v[18:19], v[18:19], 1.0 op_sel_hi:[1,0]
	v_pk_mul_f32 v[14:15], v[8:9], v[14:15]
	v_div_scale_f32 v20, s[0:1], v19, v19, v69
	v_rcp_f32_e32 v21, v20
	v_pk_mul_f32 v[10:11], v[4:5], v[10:11]
	v_pk_mul_f32 v[14:15], v[54:55], v[14:15]
	v_fma_f32 v22, -v20, v21, 1.0
	v_fmac_f32_e32 v21, v22, v21
	v_div_scale_f32 v22, vcc, v69, v19, v69
	v_mul_f32_e32 v23, v22, v21
	v_fma_f32 v24, -v20, v23, v22
	v_fmac_f32_e32 v23, v24, v21
	v_fma_f32 v20, -v20, v23, v22
	v_div_fmas_f32 v20, v20, v21, v23
	v_div_fixup_f32 v19, v20, v19, v69
	v_div_scale_f32 v20, s[0:1], v18, v18, v68
	v_rcp_f32_e32 v21, v20
	s_nop 0
	v_fma_f32 v22, -v20, v21, 1.0
	v_fmac_f32_e32 v21, v22, v21
	v_div_scale_f32 v22, vcc, v68, v18, v68
	v_mul_f32_e32 v23, v22, v21
	v_fma_f32 v24, -v20, v23, v22
	v_fmac_f32_e32 v23, v24, v21
	v_fma_f32 v20, -v20, v23, v22
	v_div_fmas_f32 v20, v20, v21, v23
	v_div_fixup_f32 v18, v20, v18, v68
	v_pk_mul_f32 v[18:19], v[18:19], v[10:11]
	v_cvt_pk_bf16_f32 v10, v12, v13
	v_cvt_pk_bf16_f32 v11, v14, v15
	v_cvt_pk_bf16_f32 v12, v16, v17
	v_cvt_pk_bf16_f32 v13, v18, v19
	global_store_dwordx4 v[66:67], v[10:13], off
	s_cbranch_scc0 .LBB0_726
	s_branch .LBB0_401
